# v51 + prologue loads overlapped + relaxed first-iteration waits + redundant post-barrier lgkmcnt(0) removed (stack of three neutral-in-isolation edits)
# speedup vs baseline: 1.0019x; 1.0019x over previous
.Lrlx0_0:
	s_waitcnt lgkmcnt(0)
	s_barrier
	v_mfma_i32_16x16x64_i8 v[174:177], v[2:5], v[98:101], 0
	v_mfma_i32_16x16x64_i8 v[174:177], v[6:9], v[102:105], v[174:177]
	v_mfma_i32_16x16x64_i8 v[170:173], v[10:13], v[98:101], 0
	v_mfma_i32_16x16x64_i8 v[170:173], v[14:17], v[102:105], v[170:173]
	v_mfma_i32_16x16x64_i8 v[158:161], v[2:5], v[106:109], 0
	v_mfma_i32_16x16x64_i8 v[158:161], v[6:9], v[110:113], v[158:161]
	v_mfma_i32_16x16x64_i8 v[154:157], v[10:13], v[106:109], 0
	v_mfma_i32_16x16x64_i8 v[154:157], v[14:17], v[110:113], v[154:157]
	v_mfma_i32_16x16x64_i8 v[142:145], v[2:5], v[178:181], 0
	v_mfma_i32_16x16x64_i8 v[142:145], v[6:9], v[182:185], v[142:145]
	v_mfma_i32_16x16x64_i8 v[138:141], v[10:13], v[178:181], 0
	v_mfma_i32_16x16x64_i8 v[138:141], v[14:17], v[182:185], v[138:141]
	v_mfma_i32_16x16x64_i8 v[126:129], v[2:5], v[186:189], 0
	v_mfma_i32_16x16x64_i8 v[126:129], v[6:9], v[190:193], v[126:129]
	v_mfma_i32_16x16x64_i8 v[122:125], v[10:13], v[186:189], 0
	v_mfma_i32_16x16x64_i8 v[122:125], v[14:17], v[190:193], v[122:125]
	v_mfma_i32_16x16x64_i8 v[166:169], v[18:21], v[98:101], 0
	v_mfma_i32_16x16x64_i8 v[166:169], v[22:25], v[102:105], v[166:169]
	v_mfma_i32_16x16x64_i8 v[98:101], v[26:29], v[98:101], 0
	v_mfma_i32_16x16x64_i8 v[98:101], v[30:33], v[102:105], v[98:101]
	v_mfma_i32_16x16x64_i8 v[102:105], v[18:21], v[106:109], 0
	v_mfma_i32_16x16x64_i8 v[102:105], v[22:25], v[110:113], v[102:105]
	v_mfma_i32_16x16x64_i8 v[106:109], v[26:29], v[106:109], 0
	v_mfma_i32_16x16x64_i8 v[106:109], v[30:33], v[110:113], v[106:109]
	v_mfma_i32_16x16x64_i8 v[130:133], v[26:29], v[178:181], 0
	v_mfma_i32_16x16x64_i8 v[130:133], v[30:33], v[182:185], v[130:133]
	v_mfma_i32_16x16x64_i8 v[118:121], v[18:21], v[186:189], 0
	v_mfma_i32_16x16x64_i8 v[118:121], v[22:25], v[190:193], v[118:121]
	v_mfma_i32_16x16x64_i8 v[114:117], v[26:29], v[186:189], 0
	v_mfma_i32_16x16x64_i8 v[114:117], v[30:33], v[190:193], v[114:117]
	v_mfma_i32_16x16x64_i8 v[110:113], v[18:21], v[178:181], 0
	v_mfma_i32_16x16x64_i8 v[110:113], v[22:25], v[182:185], v[110:113]
	s_barrier
	s_add_i32 s81, s70, s41
	v_lshl_add_u64 v[226:227], s[6:7], 0, v[196:197]
	s_mov_b32 m0, s81
	ds_read_b128 v[134:137], v236 offset:16384
	ds_read_b128 v[146:149], v236 offset:17408
	ds_read_b128 v[150:153], v236 offset:18432
	ds_read_b128 v[162:165], v236 offset:19456
	ds_read_b128 v[178:181], v236 offset:20480
	ds_read_b128 v[182:185], v236 offset:21504
	ds_read_b128 v[186:189], v236 offset:22528
	ds_read_b128 v[190:193], v236 offset:23552
	global_load_lds_dwordx4 v[226:227], off
	s_add_i32 m0, s81, 0x2000
	s_add_u32 s82, s6, 0x80000
	v_lshl_add_u64 v[244:245], s[6:7], 0, v[198:199]
	s_addc_u32 s83, s7, 0
	s_add_i32 s81, s71, s41
	global_load_lds_dwordx4 v[244:245], off
	v_lshl_add_u64 v[214:215], s[82:83], 0, v[196:197]
	s_mov_b32 m0, s81
	v_lshl_add_u64 v[246:247], s[8:9], 0, v[196:197]
	global_load_lds_dwordx4 v[214:215], off
	v_lshl_add_u64 v[214:215], s[82:83], 0, v[198:199]
	s_add_i32 m0, s81, 0x2000
	v_lshl_add_u64 v[248:249], s[8:9], 0, v[198:199]
	global_load_lds_dwordx4 v[214:215], off
	s_mov_b32 m0, s43
	s_nop 0
	global_load_lds_dwordx4 v[246:247], off
	s_mov_b32 m0, s57
	s_nop 0
	global_load_lds_dwordx4 v[248:249], off
	s_waitcnt vmcnt(24)
	s_cmp_lg_u32 s18, 0
	s_cbranch_scc1 .Lrlx0_1
	s_waitcnt vmcnt(8)
.Lrlx0_1:
	s_waitcnt lgkmcnt(0)
	s_barrier
	v_mfma_i32_16x16x64_i8 v[94:97], v[2:5], v[134:137], 0
	v_mfma_i32_16x16x64_i8 v[94:97], v[6:9], v[146:149], v[94:97]
	v_mfma_i32_16x16x64_i8 v[90:93], v[10:13], v[134:137], 0
	v_mfma_i32_16x16x64_i8 v[90:93], v[14:17], v[146:149], v[90:93]
	v_mfma_i32_16x16x64_i8 v[78:81], v[2:5], v[150:153], 0
	v_mfma_i32_16x16x64_i8 v[78:81], v[6:9], v[162:165], v[78:81]
	v_mfma_i32_16x16x64_i8 v[74:77], v[10:13], v[150:153], 0
	v_mfma_i32_16x16x64_i8 v[74:77], v[14:17], v[162:165], v[74:77]
	v_mfma_i32_16x16x64_i8 v[62:65], v[2:5], v[178:181], 0
	v_mfma_i32_16x16x64_i8 v[62:65], v[6:9], v[182:185], v[62:65]
	v_mfma_i32_16x16x64_i8 v[58:61], v[10:13], v[178:181], 0
	v_mfma_i32_16x16x64_i8 v[58:61], v[14:17], v[182:185], v[58:61]
	v_mfma_i32_16x16x64_i8 v[2:5], v[2:5], v[186:189], 0
	v_mfma_i32_16x16x64_i8 v[2:5], v[6:9], v[190:193], v[2:5]
	v_mfma_i32_16x16x64_i8 v[6:9], v[10:13], v[186:189], 0
	v_mfma_i32_16x16x64_i8 v[6:9], v[14:17], v[190:193], v[6:9]
	v_mfma_i32_16x16x64_i8 v[42:45], v[18:21], v[150:153], 0
	v_mfma_i32_16x16x64_i8 v[70:73], v[22:25], v[162:165], v[42:45]
	v_mfma_i32_16x16x64_i8 v[42:45], v[26:29], v[150:153], 0
	v_mfma_i32_16x16x64_i8 v[66:69], v[30:33], v[162:165], v[42:45]
	v_mfma_i32_16x16x64_i8 v[42:45], v[18:21], v[178:181], 0
	v_mfma_i32_16x16x64_i8 v[54:57], v[22:25], v[182:185], v[42:45]
	v_mfma_i32_16x16x64_i8 v[10:13], v[18:21], v[134:137], 0
	v_mfma_i32_16x16x64_i8 v[10:13], v[22:25], v[146:149], v[10:13]
	v_mfma_i32_16x16x64_i8 v[42:45], v[26:29], v[178:181], 0
	v_mfma_i32_16x16x64_i8 v[50:53], v[30:33], v[182:185], v[42:45]
	v_mfma_i32_16x16x64_i8 v[18:21], v[18:21], v[186:189], 0
	v_mfma_i32_16x16x64_i8 v[18:21], v[22:25], v[190:193], v[18:21]
	v_mfma_i32_16x16x64_i8 v[14:17], v[26:29], v[134:137], 0
	v_mfma_i32_16x16x64_i8 v[14:17], v[30:33], v[146:149], v[14:17]
	v_mfma_i32_16x16x64_i8 v[22:25], v[26:29], v[186:189], 0
	v_mfma_i32_16x16x64_i8 v[22:25], v[30:33], v[190:193], v[22:25]
	s_barrier
	s_add_i32 s81, 0, 0x18000
	s_add_i32 s82, 0, 0x1c000
	v_add_u32_e32 v38, s81, v229
	v_add_u32_e32 v42, s82, v229
	ds_read_b128 v[26:29], v38
	ds_read_b128 v[30:33], v38 offset:1024
	ds_read_b128 v[34:37], v38 offset:2048
	ds_read_b128 v[38:41], v38 offset:3072
	ds_read_b128 v[178:181], v42
	ds_read_b128 v[182:185], v42 offset:1024
	ds_read_b128 v[186:189], v42 offset:2048
	ds_read_b128 v[190:193], v42 offset:3072
	s_add_u32 s8, s8, 0x80000
	s_addc_u32 s9, s9, 0
	s_mov_b32 m0, s60
	v_lshl_add_u64 v[134:135], s[8:9], 0, v[196:197]
	ds_read_b128 v[42:45], v236 offset:32768
	ds_read_b128 v[46:49], v236 offset:33792
	ds_read_b128 v[82:85], v236 offset:34816
	ds_read_b128 v[86:89], v236 offset:35840
	ds_read_b128 v[214:217], v236 offset:36864
	ds_read_b128 v[218:221], v236 offset:37888
	ds_read_b128 v[222:225], v236 offset:38912
	ds_read_b128 v[240:243], v236 offset:39936
	global_load_lds_dwordx4 v[134:135], off
	v_lshl_add_u64 v[134:135], s[8:9], 0, v[198:199]
	s_mov_b32 m0, s61
	s_nop 0
	global_load_lds_dwordx4 v[134:135], off
	s_waitcnt vmcnt(8)
	s_waitcnt lgkmcnt(0)
	s_barrier
	v_mfma_i32_16x16x64_i8 v[134:137], v[26:29], v[42:45], v[174:177]
	v_mfma_i32_16x16x64_i8 v[174:177], v[30:33], v[46:49], v[134:137]
	v_mfma_i32_16x16x64_i8 v[134:137], v[34:37], v[42:45], v[170:173]
	v_mfma_i32_16x16x64_i8 v[170:173], v[38:41], v[46:49], v[134:137]
	v_mfma_i32_16x16x64_i8 v[134:137], v[26:29], v[82:85], v[158:161]
	v_mfma_i32_16x16x64_i8 v[158:161], v[30:33], v[86:89], v[134:137]
	v_mfma_i32_16x16x64_i8 v[134:137], v[34:37], v[82:85], v[154:157]
	v_mfma_i32_16x16x64_i8 v[154:157], v[38:41], v[86:89], v[134:137]
	v_mfma_i32_16x16x64_i8 v[134:137], v[26:29], v[214:217], v[142:145]
	v_mfma_i32_16x16x64_i8 v[142:145], v[30:33], v[218:221], v[134:137]
	v_mfma_i32_16x16x64_i8 v[134:137], v[34:37], v[214:217], v[138:141]
	v_mfma_i32_16x16x64_i8 v[138:141], v[38:41], v[218:221], v[134:137]
	v_mfma_i32_16x16x64_i8 v[126:129], v[26:29], v[222:225], v[126:129]
	v_mfma_i32_16x16x64_i8 v[126:129], v[30:33], v[240:243], v[126:129]
	v_mfma_i32_16x16x64_i8 v[122:125], v[34:37], v[222:225], v[122:125]
	v_mfma_i32_16x16x64_i8 v[122:125], v[38:41], v[240:243], v[122:125]
	v_mfma_i32_16x16x64_i8 v[134:137], v[178:181], v[42:45], v[166:169]
	v_mfma_i32_16x16x64_i8 v[166:169], v[182:185], v[46:49], v[134:137]
	v_mfma_i32_16x16x64_i8 v[42:45], v[186:189], v[42:45], v[98:101]
	v_mfma_i32_16x16x64_i8 v[162:165], v[190:193], v[46:49], v[42:45]
	v_mfma_i32_16x16x64_i8 v[42:45], v[178:181], v[82:85], v[102:105]
	v_mfma_i32_16x16x64_i8 v[150:153], v[182:185], v[86:89], v[42:45]
	v_mfma_i32_16x16x64_i8 v[42:45], v[186:189], v[82:85], v[106:109]
	v_mfma_i32_16x16x64_i8 v[146:149], v[190:193], v[86:89], v[42:45]
	v_mfma_i32_16x16x64_i8 v[42:45], v[178:181], v[214:217], v[110:113]
	v_mfma_i32_16x16x64_i8 v[134:137], v[182:185], v[218:221], v[42:45]
	v_mfma_i32_16x16x64_i8 v[42:45], v[186:189], v[214:217], v[130:133]
	v_mfma_i32_16x16x64_i8 v[130:133], v[190:193], v[218:221], v[42:45]
	v_mfma_i32_16x16x64_i8 v[42:45], v[178:181], v[222:225], v[118:121]
	v_mfma_i32_16x16x64_i8 v[118:121], v[182:185], v[240:243], v[42:45]
	v_mfma_i32_16x16x64_i8 v[42:45], v[186:189], v[222:225], v[114:117]
	v_mfma_i32_16x16x64_i8 v[114:117], v[190:193], v[240:243], v[42:45]
	s_barrier
	s_add_i32 s8, s81, s41
	s_nop 3
	v_lshl_add_u64 v[42:43], v[226:227], 0, s[24:25]
	s_mov_b32 m0, s8
	ds_read_b128 v[82:85], v236 offset:49152
	ds_read_b128 v[98:101], v236 offset:50176
	ds_read_b128 v[102:105], v236 offset:51200
	ds_read_b128 v[106:109], v236 offset:52224
	ds_read_b128 v[110:113], v236 offset:53248
	ds_read_b128 v[214:217], v236 offset:54272
	ds_read_b128 v[218:221], v236 offset:55296
	ds_read_b128 v[222:225], v236 offset:56320
	global_load_lds_dwordx4 v[42:43], off
	s_add_i32 m0, s8, 0x2000
	s_add_u32 s6, s6, 0x80080
	v_lshl_add_u64 v[42:43], v[244:245], 0, s[24:25]
	s_addc_u32 s7, s7, 0
	s_add_i32 s8, s82, s41
	global_load_lds_dwordx4 v[42:43], off
	v_lshl_add_u64 v[42:43], s[6:7], 0, v[196:197]
	s_mov_b32 m0, s8
	s_nop 0
	global_load_lds_dwordx4 v[42:43], off
	v_lshl_add_u64 v[42:43], s[6:7], 0, v[198:199]
	s_add_i32 m0, s8, 0x2000
	s_nop 0
	global_load_lds_dwordx4 v[42:43], off
	v_lshl_add_u64 v[42:43], v[246:247], 0, s[24:25]
	s_mov_b32 m0, s63
	s_nop 0
	global_load_lds_dwordx4 v[42:43], off
	v_lshl_add_u64 v[42:43], v[248:249], 0, s[24:25]
	s_mov_b32 m0, s64
	s_nop 0
	global_load_lds_dwordx4 v[42:43], off
	s_waitcnt vmcnt(8)
	s_waitcnt lgkmcnt(0)
	s_barrier
	v_mfma_i32_16x16x64_i8 v[42:45], v[26:29], v[82:85], v[94:97]
	v_mfma_i32_16x16x64_i8 v[94:97], v[30:33], v[98:101], v[42:45]
	v_mfma_i32_16x16x64_i8 v[42:45], v[34:37], v[82:85], v[90:93]
	v_mfma_i32_16x16x64_i8 v[90:93], v[38:41], v[98:101], v[42:45]
	v_mfma_i32_16x16x64_i8 v[42:45], v[26:29], v[102:105], v[78:81]
	v_mfma_i32_16x16x64_i8 v[78:81], v[30:33], v[106:109], v[42:45]
	v_mfma_i32_16x16x64_i8 v[42:45], v[34:37], v[102:105], v[74:77]
	v_mfma_i32_16x16x64_i8 v[74:77], v[38:41], v[106:109], v[42:45]
	v_mfma_i32_16x16x64_i8 v[42:45], v[26:29], v[110:113], v[62:65]
	v_mfma_i32_16x16x64_i8 v[62:65], v[30:33], v[214:217], v[42:45]
	v_mfma_i32_16x16x64_i8 v[2:5], v[26:29], v[218:221], v[2:5]
	v_mfma_i32_16x16x64_i8 v[46:49], v[30:33], v[222:225], v[2:5]
	v_mfma_i32_16x16x64_i8 v[42:45], v[34:37], v[110:113], v[58:61]
	v_mfma_i32_16x16x64_i8 v[58:61], v[38:41], v[214:217], v[42:45]
	v_mfma_i32_16x16x64_i8 v[2:5], v[34:37], v[218:221], v[6:9]
	v_mfma_i32_16x16x64_i8 v[42:45], v[38:41], v[222:225], v[2:5]
	v_mfma_i32_16x16x64_i8 v[2:5], v[178:181], v[82:85], v[10:13]
	v_mfma_i32_16x16x64_i8 v[86:89], v[182:185], v[98:101], v[2:5]
	v_mfma_i32_16x16x64_i8 v[2:5], v[186:189], v[82:85], v[14:17]
	v_mfma_i32_16x16x64_i8 v[82:85], v[190:193], v[98:101], v[2:5]
	v_mfma_i32_16x16x64_i8 v[2:5], v[178:181], v[102:105], v[70:73]
	v_mfma_i32_16x16x64_i8 v[70:73], v[182:185], v[106:109], v[2:5]
	v_mfma_i32_16x16x64_i8 v[2:5], v[186:189], v[102:105], v[66:69]
	v_mfma_i32_16x16x64_i8 v[66:69], v[190:193], v[106:109], v[2:5]
	v_mfma_i32_16x16x64_i8 v[2:5], v[178:181], v[110:113], v[54:57]
	v_mfma_i32_16x16x64_i8 v[54:57], v[182:185], v[214:217], v[2:5]
	v_mfma_i32_16x16x64_i8 v[2:5], v[186:189], v[110:113], v[50:53]
	v_mfma_i32_16x16x64_i8 v[50:53], v[190:193], v[214:217], v[2:5]
	v_mfma_i32_16x16x64_i8 v[2:5], v[178:181], v[218:221], v[18:21]
	v_mfma_i32_16x16x64_i8 v[38:41], v[182:185], v[222:225], v[2:5]
	v_mfma_i32_16x16x64_i8 v[2:5], v[186:189], v[218:221], v[22:25]
	v_mfma_i32_16x16x64_i8 v[34:37], v[190:193], v[222:225], v[2:5]
	s_barrier
	s_add_i32 s80, s80, 2
	s_add_u32 s4, s4, 0x100
	s_addc_u32 s5, s5, 0
	s_add_u32 s78, s78, 0x100
	s_addc_u32 s79, s79, 0
	s_cmp_gt_u32 s80, 29

.Lrlx1_0:
	s_waitcnt lgkmcnt(0)
	s_barrier
	v_mfma_i32_16x16x64_i8 v[142:145], v[106:109], v[162:165], 0
	v_mfma_i32_16x16x64_i8 v[142:145], v[114:117], v[182:185], v[142:145]
	v_mfma_i32_16x16x64_i8 v[138:141], v[122:125], v[162:165], 0
	v_mfma_i32_16x16x64_i8 v[138:141], v[130:133], v[182:185], v[138:141]
	v_mfma_i32_16x16x64_i8 v[118:121], v[106:109], v[186:189], 0
	v_mfma_i32_16x16x64_i8 v[118:121], v[114:117], v[206:209], v[118:121]
	v_mfma_i32_16x16x64_i8 v[110:113], v[122:125], v[186:189], 0
	v_mfma_i32_16x16x64_i8 v[110:113], v[130:133], v[206:209], v[110:113]
	v_mfma_i32_16x16x64_i8 v[94:97], v[106:109], v[210:213], 0
	v_mfma_i32_16x16x64_i8 v[94:97], v[114:117], v[214:217], v[94:97]
	v_mfma_i32_16x16x64_i8 v[90:93], v[122:125], v[210:213], 0
	v_mfma_i32_16x16x64_i8 v[90:93], v[130:133], v[214:217], v[90:93]
	v_mfma_i32_16x16x64_i8 v[78:81], v[106:109], v[218:221], 0
	v_mfma_i32_16x16x64_i8 v[78:81], v[114:117], v[222:225], v[78:81]
	v_mfma_i32_16x16x64_i8 v[74:77], v[122:125], v[218:221], 0
	v_mfma_i32_16x16x64_i8 v[74:77], v[130:133], v[222:225], v[74:77]
	v_mfma_i32_16x16x64_i8 v[134:137], v[146:149], v[162:165], 0
	v_mfma_i32_16x16x64_i8 v[134:137], v[150:153], v[182:185], v[134:137]
	v_mfma_i32_16x16x64_i8 v[126:129], v[154:157], v[162:165], 0
	v_mfma_i32_16x16x64_i8 v[126:129], v[158:161], v[182:185], v[126:129]
	v_mfma_i32_16x16x64_i8 v[102:105], v[146:149], v[186:189], 0
	v_mfma_i32_16x16x64_i8 v[102:105], v[150:153], v[206:209], v[102:105]
	v_mfma_i32_16x16x64_i8 v[98:101], v[154:157], v[186:189], 0
	v_mfma_i32_16x16x64_i8 v[98:101], v[158:161], v[206:209], v[98:101]
	v_mfma_i32_16x16x64_i8 v[86:89], v[146:149], v[210:213], 0
	v_mfma_i32_16x16x64_i8 v[86:89], v[150:153], v[214:217], v[86:89]
	v_mfma_i32_16x16x64_i8 v[82:85], v[154:157], v[210:213], 0
	v_mfma_i32_16x16x64_i8 v[82:85], v[158:161], v[214:217], v[82:85]
	v_mfma_i32_16x16x64_i8 v[70:73], v[146:149], v[218:221], 0
	v_mfma_i32_16x16x64_i8 v[70:73], v[150:153], v[222:225], v[70:73]
	v_mfma_i32_16x16x64_i8 v[66:69], v[154:157], v[218:221], 0
	v_mfma_i32_16x16x64_i8 v[66:69], v[158:161], v[222:225], v[66:69]
	s_barrier
	s_add_i32 s71, s63, s39
	v_lshl_add_u64 v[194:195], s[30:31], 0, v[168:169]
	s_mov_b32 m0, s71
	ds_read_b128 v[162:165], v204 offset:16384
	ds_read_b128 v[182:185], v204 offset:17408
	ds_read_b128 v[186:189], v204 offset:18432
	ds_read_b128 v[206:209], v204 offset:19456
	ds_read_b128 v[210:213], v204 offset:20480
	ds_read_b128 v[214:217], v204 offset:21504
	ds_read_b128 v[218:221], v204 offset:22528
	ds_read_b128 v[222:225], v204 offset:23552
	global_load_lds_dwordx4 v[194:195], off
	s_add_i32 m0, s71, 0x2000
	s_add_u32 s72, s30, 0x80000
	v_lshl_add_u64 v[198:199], s[30:31], 0, v[172:173]
	s_addc_u32 s73, s31, 0
	s_add_i32 s71, s64, s39
	global_load_lds_dwordx4 v[198:199], off
	v_lshl_add_u64 v[202:203], s[72:73], 0, v[168:169]
	s_mov_b32 m0, s71
	v_lshl_add_u64 v[226:227], s[34:35], 0, v[170:171]
	global_load_lds_dwordx4 v[202:203], off
	v_lshl_add_u64 v[202:203], s[72:73], 0, v[172:173]
	s_add_i32 m0, s71, 0x2000
	s_nop 0
	global_load_lds_dwordx4 v[202:203], off
	v_lshl_add_u64 v[202:203], s[34:35], 0, v[166:167]
	s_mov_b32 m0, s19
	s_nop 0
	global_load_lds_dwordx4 v[202:203], off
	s_mov_b32 m0, s40
	s_nop 0
	global_load_lds_dwordx4 v[226:227], off
	s_waitcnt vmcnt(24)
	s_cmp_lg_u32 s43, 1
	s_cbranch_scc1 .Lrlx1_1
	s_waitcnt vmcnt(8)
.Lrlx1_1:
	s_waitcnt lgkmcnt(0)
	s_barrier
	v_mfma_i32_16x16x64_i8 v[62:65], v[106:109], v[162:165], 0
	v_mfma_i32_16x16x64_i8 v[62:65], v[114:117], v[182:185], v[62:65]
	v_mfma_i32_16x16x64_i8 v[58:61], v[122:125], v[162:165], 0
	v_mfma_i32_16x16x64_i8 v[58:61], v[130:133], v[182:185], v[58:61]
	v_mfma_i32_16x16x64_i8 v[46:49], v[106:109], v[186:189], 0
	v_mfma_i32_16x16x64_i8 v[46:49], v[114:117], v[206:209], v[46:49]
	v_mfma_i32_16x16x64_i8 v[42:45], v[122:125], v[186:189], 0
	v_mfma_i32_16x16x64_i8 v[42:45], v[130:133], v[206:209], v[42:45]
	v_mfma_i32_16x16x64_i8 v[30:33], v[106:109], v[210:213], 0
	v_mfma_i32_16x16x64_i8 v[30:33], v[114:117], v[214:217], v[30:33]
	v_mfma_i32_16x16x64_i8 v[26:29], v[122:125], v[210:213], 0
	v_mfma_i32_16x16x64_i8 v[26:29], v[130:133], v[214:217], v[26:29]
	v_mfma_i32_16x16x64_i8 v[14:17], v[106:109], v[218:221], 0
	v_mfma_i32_16x16x64_i8 v[14:17], v[114:117], v[222:225], v[14:17]
	v_mfma_i32_16x16x64_i8 v[10:13], v[122:125], v[218:221], 0
	v_mfma_i32_16x16x64_i8 v[10:13], v[130:133], v[222:225], v[10:13]
	v_mfma_i32_16x16x64_i8 v[54:57], v[146:149], v[162:165], 0
	v_mfma_i32_16x16x64_i8 v[54:57], v[150:153], v[182:185], v[54:57]
	v_mfma_i32_16x16x64_i8 v[50:53], v[154:157], v[162:165], 0
	v_mfma_i32_16x16x64_i8 v[50:53], v[158:161], v[182:185], v[50:53]
	v_mfma_i32_16x16x64_i8 v[38:41], v[146:149], v[186:189], 0
	v_mfma_i32_16x16x64_i8 v[38:41], v[150:153], v[206:209], v[38:41]
	v_mfma_i32_16x16x64_i8 v[34:37], v[154:157], v[186:189], 0
	v_mfma_i32_16x16x64_i8 v[34:37], v[158:161], v[206:209], v[34:37]
	v_mfma_i32_16x16x64_i8 v[22:25], v[146:149], v[210:213], 0
	v_mfma_i32_16x16x64_i8 v[22:25], v[150:153], v[214:217], v[22:25]
	v_mfma_i32_16x16x64_i8 v[18:21], v[154:157], v[210:213], 0
	v_mfma_i32_16x16x64_i8 v[18:21], v[158:161], v[214:217], v[18:21]
	v_mfma_i32_16x16x64_i8 v[6:9], v[146:149], v[218:221], 0
	v_mfma_i32_16x16x64_i8 v[6:9], v[150:153], v[222:225], v[6:9]
	v_mfma_i32_16x16x64_i8 v[2:5], v[154:157], v[218:221], 0
	v_mfma_i32_16x16x64_i8 v[2:5], v[158:161], v[222:225], v[2:5]
	s_barrier
	s_add_i32 s71, 0, 0x18000
	s_add_i32 s72, 0, 0x1c000
	v_add_u32_e32 v130, s71, v193
	v_add_u32_e32 v158, s72, v193
	ds_read_b128 v[106:109], v130
	ds_read_b128 v[114:117], v130 offset:1024
	ds_read_b128 v[122:125], v130 offset:2048
	ds_read_b128 v[130:133], v130 offset:3072
	ds_read_b128 v[146:149], v158
	ds_read_b128 v[150:153], v158 offset:1024
	ds_read_b128 v[154:157], v158 offset:2048
	ds_read_b128 v[158:161], v158 offset:3072
	s_add_u32 s34, s34, 0x80000
	s_addc_u32 s35, s35, 0
	s_mov_b32 m0, s41
	v_lshl_add_u64 v[228:229], s[34:35], 0, v[166:167]
	ds_read_b128 v[162:165], v204 offset:32768
	ds_read_b128 v[182:185], v204 offset:33792
	ds_read_b128 v[186:189], v204 offset:34816
	ds_read_b128 v[206:209], v204 offset:35840
	ds_read_b128 v[210:213], v204 offset:36864
	ds_read_b128 v[214:217], v204 offset:37888
	ds_read_b128 v[218:221], v204 offset:38912
	ds_read_b128 v[222:225], v204 offset:39936
	global_load_lds_dwordx4 v[228:229], off
	v_lshl_add_u64 v[228:229], s[34:35], 0, v[170:171]
	s_mov_b32 m0, s42
	s_nop 0
	global_load_lds_dwordx4 v[228:229], off
	s_waitcnt vmcnt(8)
	s_waitcnt lgkmcnt(0)
	s_barrier
	v_mfma_i32_16x16x64_i8 v[142:145], v[106:109], v[162:165], v[142:145]
	v_mfma_i32_16x16x64_i8 v[142:145], v[114:117], v[182:185], v[142:145]
	v_mfma_i32_16x16x64_i8 v[138:141], v[122:125], v[162:165], v[138:141]
	v_mfma_i32_16x16x64_i8 v[138:141], v[130:133], v[182:185], v[138:141]
	v_mfma_i32_16x16x64_i8 v[118:121], v[106:109], v[186:189], v[118:121]
	v_mfma_i32_16x16x64_i8 v[118:121], v[114:117], v[206:209], v[118:121]
	v_mfma_i32_16x16x64_i8 v[110:113], v[122:125], v[186:189], v[110:113]
	v_mfma_i32_16x16x64_i8 v[110:113], v[130:133], v[206:209], v[110:113]
	v_mfma_i32_16x16x64_i8 v[94:97], v[106:109], v[210:213], v[94:97]
	v_mfma_i32_16x16x64_i8 v[94:97], v[114:117], v[214:217], v[94:97]
	v_mfma_i32_16x16x64_i8 v[90:93], v[122:125], v[210:213], v[90:93]
	v_mfma_i32_16x16x64_i8 v[90:93], v[130:133], v[214:217], v[90:93]
	v_mfma_i32_16x16x64_i8 v[78:81], v[106:109], v[218:221], v[78:81]
	v_mfma_i32_16x16x64_i8 v[78:81], v[114:117], v[222:225], v[78:81]
	v_mfma_i32_16x16x64_i8 v[74:77], v[122:125], v[218:221], v[74:77]
	v_mfma_i32_16x16x64_i8 v[74:77], v[130:133], v[222:225], v[74:77]
	v_mfma_i32_16x16x64_i8 v[134:137], v[146:149], v[162:165], v[134:137]
	v_mfma_i32_16x16x64_i8 v[134:137], v[150:153], v[182:185], v[134:137]
	v_mfma_i32_16x16x64_i8 v[126:129], v[154:157], v[162:165], v[126:129]
	v_mfma_i32_16x16x64_i8 v[126:129], v[158:161], v[182:185], v[126:129]
	v_mfma_i32_16x16x64_i8 v[102:105], v[146:149], v[186:189], v[102:105]
	v_mfma_i32_16x16x64_i8 v[102:105], v[150:153], v[206:209], v[102:105]
	v_mfma_i32_16x16x64_i8 v[98:101], v[154:157], v[186:189], v[98:101]
	v_mfma_i32_16x16x64_i8 v[98:101], v[158:161], v[206:209], v[98:101]
	v_mfma_i32_16x16x64_i8 v[86:89], v[146:149], v[210:213], v[86:89]
	v_mfma_i32_16x16x64_i8 v[86:89], v[150:153], v[214:217], v[86:89]
	v_mfma_i32_16x16x64_i8 v[82:85], v[154:157], v[210:213], v[82:85]
	v_mfma_i32_16x16x64_i8 v[82:85], v[158:161], v[214:217], v[82:85]
	v_mfma_i32_16x16x64_i8 v[70:73], v[146:149], v[218:221], v[70:73]
	v_mfma_i32_16x16x64_i8 v[70:73], v[150:153], v[222:225], v[70:73]
	v_mfma_i32_16x16x64_i8 v[66:69], v[154:157], v[218:221], v[66:69]
	v_mfma_i32_16x16x64_i8 v[66:69], v[158:161], v[222:225], v[66:69]
	s_barrier
	s_add_i32 s34, s71, s39
	v_lshl_add_u64 v[194:195], v[194:195], 0, s[10:11]
	s_mov_b32 m0, s34
	ds_read_b128 v[162:165], v204 offset:49152
	ds_read_b128 v[182:185], v204 offset:50176
	ds_read_b128 v[186:189], v204 offset:51200
	ds_read_b128 v[206:209], v204 offset:52224
	ds_read_b128 v[210:213], v204 offset:53248
	ds_read_b128 v[214:217], v204 offset:54272
	ds_read_b128 v[218:221], v204 offset:55296
	ds_read_b128 v[222:225], v204 offset:56320
	global_load_lds_dwordx4 v[194:195], off
	s_add_i32 m0, s34, 0x2000
	s_add_u32 s30, s30, 0x80080
	v_lshl_add_u64 v[194:195], v[198:199], 0, s[10:11]
	s_addc_u32 s31, s31, 0
	s_add_i32 s34, s72, s39
	global_load_lds_dwordx4 v[194:195], off
	v_lshl_add_u64 v[194:195], s[30:31], 0, v[168:169]
	s_mov_b32 m0, s34
	s_nop 0
	global_load_lds_dwordx4 v[194:195], off
	v_lshl_add_u64 v[194:195], s[30:31], 0, v[172:173]
	s_add_i32 m0, s34, 0x2000
	s_nop 0
	global_load_lds_dwordx4 v[194:195], off
	v_lshl_add_u64 v[194:195], v[202:203], 0, s[10:11]
	s_mov_b32 m0, s60
	s_nop 0
	global_load_lds_dwordx4 v[194:195], off
	v_lshl_add_u64 v[194:195], v[226:227], 0, s[10:11]
	s_mov_b32 m0, s61
	s_nop 0
	global_load_lds_dwordx4 v[194:195], off
	s_waitcnt vmcnt(8)
	s_waitcnt lgkmcnt(0)
	s_barrier
	v_mfma_i32_16x16x64_i8 v[62:65], v[106:109], v[162:165], v[62:65]
	v_mfma_i32_16x16x64_i8 v[62:65], v[114:117], v[182:185], v[62:65]
	v_mfma_i32_16x16x64_i8 v[58:61], v[122:125], v[162:165], v[58:61]
	v_mfma_i32_16x16x64_i8 v[58:61], v[130:133], v[182:185], v[58:61]
	v_mfma_i32_16x16x64_i8 v[46:49], v[106:109], v[186:189], v[46:49]
	v_mfma_i32_16x16x64_i8 v[46:49], v[114:117], v[206:209], v[46:49]
	v_mfma_i32_16x16x64_i8 v[42:45], v[122:125], v[186:189], v[42:45]
	v_mfma_i32_16x16x64_i8 v[42:45], v[130:133], v[206:209], v[42:45]
	v_mfma_i32_16x16x64_i8 v[30:33], v[106:109], v[210:213], v[30:33]
	v_mfma_i32_16x16x64_i8 v[30:33], v[114:117], v[214:217], v[30:33]
	v_mfma_i32_16x16x64_i8 v[26:29], v[122:125], v[210:213], v[26:29]
	v_mfma_i32_16x16x64_i8 v[26:29], v[130:133], v[214:217], v[26:29]
	v_mfma_i32_16x16x64_i8 v[14:17], v[106:109], v[218:221], v[14:17]
	v_mfma_i32_16x16x64_i8 v[14:17], v[114:117], v[222:225], v[14:17]
	v_mfma_i32_16x16x64_i8 v[10:13], v[122:125], v[218:221], v[10:13]
	v_mfma_i32_16x16x64_i8 v[10:13], v[130:133], v[222:225], v[10:13]
	v_mfma_i32_16x16x64_i8 v[54:57], v[146:149], v[162:165], v[54:57]
	v_mfma_i32_16x16x64_i8 v[54:57], v[150:153], v[182:185], v[54:57]
	v_mfma_i32_16x16x64_i8 v[50:53], v[154:157], v[162:165], v[50:53]
	v_mfma_i32_16x16x64_i8 v[50:53], v[158:161], v[182:185], v[50:53]
	v_mfma_i32_16x16x64_i8 v[38:41], v[146:149], v[186:189], v[38:41]
	v_mfma_i32_16x16x64_i8 v[38:41], v[150:153], v[206:209], v[38:41]
	v_mfma_i32_16x16x64_i8 v[34:37], v[154:157], v[186:189], v[34:37]
	v_mfma_i32_16x16x64_i8 v[34:37], v[158:161], v[206:209], v[34:37]
	v_mfma_i32_16x16x64_i8 v[22:25], v[146:149], v[210:213], v[22:25]
	v_mfma_i32_16x16x64_i8 v[22:25], v[150:153], v[214:217], v[22:25]
	v_mfma_i32_16x16x64_i8 v[18:21], v[154:157], v[210:213], v[18:21]
	v_mfma_i32_16x16x64_i8 v[18:21], v[158:161], v[214:217], v[18:21]
	v_mfma_i32_16x16x64_i8 v[6:9], v[146:149], v[218:221], v[6:9]
	v_mfma_i32_16x16x64_i8 v[6:9], v[150:153], v[222:225], v[6:9]
	v_mfma_i32_16x16x64_i8 v[2:5], v[154:157], v[218:221], v[2:5]
	v_mfma_i32_16x16x64_i8 v[2:5], v[158:161], v[222:225], v[2:5]
	s_barrier
	s_add_i32 s70, s70, 2
	s_add_u32 s28, s28, 0x100
	s_addc_u32 s29, s29, 0
	s_add_u32 s68, s68, 0x100
	s_addc_u32 s69, s69, 0
	s_cmp_gt_u32 s70, 29

.Lrlx2_0:
	s_waitcnt lgkmcnt(0)
	s_barrier
	v_mfma_i32_16x16x64_i8 v[118:121], v[130:133], v[186:189], 0
	v_mfma_i32_16x16x64_i8 v[118:121], v[134:137], v[190:193], v[118:121]
	v_mfma_i32_16x16x64_i8 v[102:105], v[162:165], v[186:189], 0
	v_mfma_i32_16x16x64_i8 v[102:105], v[166:169], v[190:193], v[102:105]
	v_mfma_i32_16x16x64_i8 v[114:117], v[130:133], v[194:197], 0
	v_mfma_i32_16x16x64_i8 v[114:117], v[134:137], v[198:201], v[114:117]
	v_mfma_i32_16x16x64_i8 v[98:101], v[162:165], v[194:197], 0
	v_mfma_i32_16x16x64_i8 v[98:101], v[166:169], v[198:201], v[98:101]
	v_mfma_i32_16x16x64_i8 v[126:129], v[130:133], v[202:205], 0
	v_mfma_i32_16x16x64_i8 v[126:129], v[134:137], v[206:209], v[126:129]
	v_mfma_i32_16x16x64_i8 v[110:113], v[162:165], v[202:205], 0
	v_mfma_i32_16x16x64_i8 v[110:113], v[166:169], v[206:209], v[110:113]
	v_mfma_i32_16x16x64_i8 v[122:125], v[130:133], v[210:213], 0
	v_mfma_i32_16x16x64_i8 v[122:125], v[134:137], v[214:217], v[122:125]
	v_mfma_i32_16x16x64_i8 v[106:109], v[162:165], v[210:213], 0
	v_mfma_i32_16x16x64_i8 v[106:109], v[166:169], v[214:217], v[106:109]
	v_mfma_i32_16x16x64_i8 v[86:89], v[170:173], v[186:189], 0
	v_mfma_i32_16x16x64_i8 v[86:89], v[174:177], v[190:193], v[86:89]
	v_mfma_i32_16x16x64_i8 v[70:73], v[178:181], v[186:189], 0
	v_mfma_i32_16x16x64_i8 v[70:73], v[182:185], v[190:193], v[70:73]
	v_mfma_i32_16x16x64_i8 v[82:85], v[170:173], v[194:197], 0
	v_mfma_i32_16x16x64_i8 v[82:85], v[174:177], v[198:201], v[82:85]
	v_mfma_i32_16x16x64_i8 v[66:69], v[178:181], v[194:197], 0
	v_mfma_i32_16x16x64_i8 v[66:69], v[182:185], v[198:201], v[66:69]
	v_mfma_i32_16x16x64_i8 v[94:97], v[170:173], v[202:205], 0
	v_mfma_i32_16x16x64_i8 v[94:97], v[174:177], v[206:209], v[94:97]
	v_mfma_i32_16x16x64_i8 v[78:81], v[178:181], v[202:205], 0
	v_mfma_i32_16x16x64_i8 v[78:81], v[182:185], v[206:209], v[78:81]
	v_mfma_i32_16x16x64_i8 v[90:93], v[170:173], v[210:213], 0
	v_mfma_i32_16x16x64_i8 v[90:93], v[174:177], v[214:217], v[90:93]
	v_mfma_i32_16x16x64_i8 v[74:77], v[178:181], v[210:213], 0
	v_mfma_i32_16x16x64_i8 v[74:77], v[182:185], v[214:217], v[74:77]
	s_barrier
	s_add_i32 s4, s97, s63
	v_lshl_add_u64 v[218:219], s[18:19], 0, v[144:145]
	s_mov_b32 m0, s4
	ds_read_b128 v[186:189], v236 offset:16384
	ds_read_b128 v[190:193], v236 offset:17408
	ds_read_b128 v[194:197], v236 offset:18432
	ds_read_b128 v[198:201], v236 offset:19456
	ds_read_b128 v[202:205], v236 offset:20480
	ds_read_b128 v[206:209], v236 offset:21504
	ds_read_b128 v[210:213], v236 offset:22528
	ds_read_b128 v[214:217], v236 offset:23552
	global_load_lds_dwordx4 v[218:219], off
	s_add_i32 m0, s4, 0x2000
	s_add_u32 s4, s18, 0x80000
	v_lshl_add_u64 v[220:221], s[18:19], 0, v[148:149]
	s_addc_u32 s5, s19, 0
	s_add_i32 s81, s0, s63
	global_load_lds_dwordx4 v[220:221], off
	v_lshl_add_u64 v[222:223], s[4:5], 0, v[144:145]
	s_mov_b32 m0, s81
	v_lshl_add_u64 v[224:225], s[56:57], 0, v[146:147]
	global_load_lds_dwordx4 v[222:223], off
	v_lshl_add_u64 v[222:223], s[4:5], 0, v[148:149]
	s_add_i32 m0, s81, 0x2000
	s_nop 0
	global_load_lds_dwordx4 v[222:223], off
	v_lshl_add_u64 v[222:223], s[56:57], 0, v[142:143]
	s_mov_b32 m0, s65
	s_nop 0
	global_load_lds_dwordx4 v[222:223], off
	s_mov_b32 m0, s66
	s_nop 0
	global_load_lds_dwordx4 v[224:225], off
	s_waitcnt vmcnt(24)
	s_cmp_lg_u32 s9, 0
	s_cbranch_scc1 .Lrlx2_1
	s_waitcnt vmcnt(8)
.Lrlx2_1:
	s_waitcnt lgkmcnt(0)
	s_barrier
	v_mfma_i32_16x16x64_i8 v[54:57], v[130:133], v[186:189], 0
	v_mfma_i32_16x16x64_i8 v[54:57], v[134:137], v[190:193], v[54:57]
	v_mfma_i32_16x16x64_i8 v[18:21], v[162:165], v[186:189], 0
	v_mfma_i32_16x16x64_i8 v[18:21], v[166:169], v[190:193], v[18:21]
	v_mfma_i32_16x16x64_i8 v[50:53], v[130:133], v[194:197], 0
	v_mfma_i32_16x16x64_i8 v[50:53], v[134:137], v[198:201], v[50:53]
	v_mfma_i32_16x16x64_i8 v[22:25], v[162:165], v[194:197], 0
	v_mfma_i32_16x16x64_i8 v[22:25], v[166:169], v[198:201], v[22:25]
	v_mfma_i32_16x16x64_i8 v[62:65], v[130:133], v[202:205], 0
	v_mfma_i32_16x16x64_i8 v[62:65], v[134:137], v[206:209], v[62:65]
	v_mfma_i32_16x16x64_i8 v[30:33], v[162:165], v[202:205], 0
	v_mfma_i32_16x16x64_i8 v[30:33], v[166:169], v[206:209], v[30:33]
	v_mfma_i32_16x16x64_i8 v[58:61], v[130:133], v[210:213], 0
	v_mfma_i32_16x16x64_i8 v[58:61], v[134:137], v[214:217], v[58:61]
	v_mfma_i32_16x16x64_i8 v[26:29], v[162:165], v[210:213], 0
	v_mfma_i32_16x16x64_i8 v[26:29], v[166:169], v[214:217], v[26:29]
	v_mfma_i32_16x16x64_i8 v[46:49], v[170:173], v[186:189], 0
	v_mfma_i32_16x16x64_i8 v[46:49], v[174:177], v[190:193], v[46:49]
	v_mfma_i32_16x16x64_i8 v[14:17], v[178:181], v[186:189], 0
	v_mfma_i32_16x16x64_i8 v[14:17], v[182:185], v[190:193], v[14:17]
	v_mfma_i32_16x16x64_i8 v[42:45], v[170:173], v[194:197], 0
	v_mfma_i32_16x16x64_i8 v[42:45], v[174:177], v[198:201], v[42:45]
	v_mfma_i32_16x16x64_i8 v[10:13], v[178:181], v[194:197], 0
	v_mfma_i32_16x16x64_i8 v[10:13], v[182:185], v[198:201], v[10:13]
	v_mfma_i32_16x16x64_i8 v[38:41], v[170:173], v[202:205], 0
	v_mfma_i32_16x16x64_i8 v[38:41], v[174:177], v[206:209], v[38:41]
	v_mfma_i32_16x16x64_i8 v[6:9], v[178:181], v[202:205], 0
	v_mfma_i32_16x16x64_i8 v[6:9], v[182:185], v[206:209], v[6:9]
	v_mfma_i32_16x16x64_i8 v[34:37], v[170:173], v[210:213], 0
	v_mfma_i32_16x16x64_i8 v[34:37], v[174:177], v[214:217], v[34:37]
	v_mfma_i32_16x16x64_i8 v[2:5], v[178:181], v[210:213], 0
	v_mfma_i32_16x16x64_i8 v[2:5], v[182:185], v[214:217], v[2:5]
	s_barrier
	s_add_i32 s81, 0, 0x18000
	s_add_i32 s82, 0, 0x1c000
	v_add_u32_e32 v166, s81, v232
	v_add_u32_e32 v182, s82, v232
	ds_read_b128 v[130:133], v166
	ds_read_b128 v[134:137], v166 offset:1024
	ds_read_b128 v[162:165], v166 offset:2048
	ds_read_b128 v[166:169], v166 offset:3072
	ds_read_b128 v[170:173], v182
	ds_read_b128 v[174:177], v182 offset:1024
	ds_read_b128 v[178:181], v182 offset:2048
	ds_read_b128 v[182:185], v182 offset:3072
	s_add_u32 s4, s56, 0x80000
	s_addc_u32 s5, s57, 0
	s_mov_b32 m0, s67
	v_lshl_add_u64 v[226:227], s[4:5], 0, v[142:143]
	ds_read_b128 v[186:189], v236 offset:32768
	ds_read_b128 v[190:193], v236 offset:33792
	ds_read_b128 v[194:197], v236 offset:34816
	ds_read_b128 v[198:201], v236 offset:35840
	ds_read_b128 v[202:205], v236 offset:36864
	ds_read_b128 v[206:209], v236 offset:37888
	ds_read_b128 v[210:213], v236 offset:38912
	ds_read_b128 v[214:217], v236 offset:39936
	global_load_lds_dwordx4 v[226:227], off
	v_lshl_add_u64 v[226:227], s[4:5], 0, v[146:147]
	s_mov_b32 m0, s68
	s_nop 0
	global_load_lds_dwordx4 v[226:227], off
	s_waitcnt vmcnt(8)
	s_waitcnt lgkmcnt(0)
	s_barrier
	v_mfma_i32_16x16x64_i8 v[118:121], v[130:133], v[186:189], v[118:121]
	v_mfma_i32_16x16x64_i8 v[118:121], v[134:137], v[190:193], v[118:121]
	v_mfma_i32_16x16x64_i8 v[102:105], v[162:165], v[186:189], v[102:105]
	v_mfma_i32_16x16x64_i8 v[102:105], v[166:169], v[190:193], v[102:105]
	v_mfma_i32_16x16x64_i8 v[114:117], v[130:133], v[194:197], v[114:117]
	v_mfma_i32_16x16x64_i8 v[114:117], v[134:137], v[198:201], v[114:117]
	v_mfma_i32_16x16x64_i8 v[98:101], v[162:165], v[194:197], v[98:101]
	v_mfma_i32_16x16x64_i8 v[98:101], v[166:169], v[198:201], v[98:101]
	v_mfma_i32_16x16x64_i8 v[126:129], v[130:133], v[202:205], v[126:129]
	v_mfma_i32_16x16x64_i8 v[126:129], v[134:137], v[206:209], v[126:129]
	v_mfma_i32_16x16x64_i8 v[110:113], v[162:165], v[202:205], v[110:113]
	v_mfma_i32_16x16x64_i8 v[110:113], v[166:169], v[206:209], v[110:113]
	v_mfma_i32_16x16x64_i8 v[122:125], v[130:133], v[210:213], v[122:125]
	v_mfma_i32_16x16x64_i8 v[122:125], v[134:137], v[214:217], v[122:125]
	v_mfma_i32_16x16x64_i8 v[106:109], v[162:165], v[210:213], v[106:109]
	v_mfma_i32_16x16x64_i8 v[106:109], v[166:169], v[214:217], v[106:109]
	v_mfma_i32_16x16x64_i8 v[86:89], v[170:173], v[186:189], v[86:89]
	v_mfma_i32_16x16x64_i8 v[86:89], v[174:177], v[190:193], v[86:89]
	v_mfma_i32_16x16x64_i8 v[70:73], v[178:181], v[186:189], v[70:73]
	v_mfma_i32_16x16x64_i8 v[70:73], v[182:185], v[190:193], v[70:73]
	v_mfma_i32_16x16x64_i8 v[82:85], v[170:173], v[194:197], v[82:85]
	v_mfma_i32_16x16x64_i8 v[82:85], v[174:177], v[198:201], v[82:85]
	v_mfma_i32_16x16x64_i8 v[66:69], v[178:181], v[194:197], v[66:69]
	v_mfma_i32_16x16x64_i8 v[66:69], v[182:185], v[198:201], v[66:69]
	v_mfma_i32_16x16x64_i8 v[94:97], v[170:173], v[202:205], v[94:97]
	v_mfma_i32_16x16x64_i8 v[94:97], v[174:177], v[206:209], v[94:97]
	v_mfma_i32_16x16x64_i8 v[78:81], v[178:181], v[202:205], v[78:81]
	v_mfma_i32_16x16x64_i8 v[78:81], v[182:185], v[206:209], v[78:81]
	v_mfma_i32_16x16x64_i8 v[90:93], v[170:173], v[210:213], v[90:93]
	v_mfma_i32_16x16x64_i8 v[90:93], v[174:177], v[214:217], v[90:93]
	v_mfma_i32_16x16x64_i8 v[74:77], v[178:181], v[210:213], v[74:77]
	v_mfma_i32_16x16x64_i8 v[74:77], v[182:185], v[214:217], v[74:77]
	s_barrier
	s_add_i32 s4, s81, s63
	v_lshl_add_u64 v[218:219], v[218:219], 0, s[22:23]
	s_mov_b32 m0, s4
	ds_read_b128 v[186:189], v236 offset:49152
	ds_read_b128 v[190:193], v236 offset:50176
	ds_read_b128 v[194:197], v236 offset:51200
	ds_read_b128 v[198:201], v236 offset:52224
	ds_read_b128 v[202:205], v236 offset:53248
	ds_read_b128 v[206:209], v236 offset:54272
	ds_read_b128 v[210:213], v236 offset:55296
	ds_read_b128 v[214:217], v236 offset:56320
	global_load_lds_dwordx4 v[218:219], off
	s_add_i32 m0, s4, 0x2000
	s_add_u32 s4, s18, 0x80080
	v_lshl_add_u64 v[218:219], v[220:221], 0, s[22:23]
	s_addc_u32 s5, s19, 0
	s_add_i32 s18, s82, s63
	global_load_lds_dwordx4 v[218:219], off
	v_lshl_add_u64 v[218:219], s[4:5], 0, v[144:145]
	s_mov_b32 m0, s18
	s_nop 0
	global_load_lds_dwordx4 v[218:219], off
	v_lshl_add_u64 v[218:219], s[4:5], 0, v[148:149]
	s_add_i32 m0, s18, 0x2000
	s_nop 0
	global_load_lds_dwordx4 v[218:219], off
	v_lshl_add_u64 v[218:219], v[222:223], 0, s[22:23]
	s_mov_b32 m0, s77
	s_nop 0
	global_load_lds_dwordx4 v[218:219], off
	v_lshl_add_u64 v[218:219], v[224:225], 0, s[22:23]
	s_mov_b32 m0, s78
	s_nop 0
	global_load_lds_dwordx4 v[218:219], off
	s_waitcnt vmcnt(8)
	s_waitcnt lgkmcnt(0)
	s_barrier
	v_mfma_i32_16x16x64_i8 v[54:57], v[130:133], v[186:189], v[54:57]
	v_mfma_i32_16x16x64_i8 v[54:57], v[134:137], v[190:193], v[54:57]
	v_mfma_i32_16x16x64_i8 v[18:21], v[162:165], v[186:189], v[18:21]
	v_mfma_i32_16x16x64_i8 v[18:21], v[166:169], v[190:193], v[18:21]
	v_mfma_i32_16x16x64_i8 v[50:53], v[130:133], v[194:197], v[50:53]
	v_mfma_i32_16x16x64_i8 v[50:53], v[134:137], v[198:201], v[50:53]
	v_mfma_i32_16x16x64_i8 v[22:25], v[162:165], v[194:197], v[22:25]
	v_mfma_i32_16x16x64_i8 v[22:25], v[166:169], v[198:201], v[22:25]
	v_mfma_i32_16x16x64_i8 v[62:65], v[130:133], v[202:205], v[62:65]
	v_mfma_i32_16x16x64_i8 v[62:65], v[134:137], v[206:209], v[62:65]
	v_mfma_i32_16x16x64_i8 v[30:33], v[162:165], v[202:205], v[30:33]
	v_mfma_i32_16x16x64_i8 v[30:33], v[166:169], v[206:209], v[30:33]
	v_mfma_i32_16x16x64_i8 v[58:61], v[130:133], v[210:213], v[58:61]
	v_mfma_i32_16x16x64_i8 v[58:61], v[134:137], v[214:217], v[58:61]
	v_mfma_i32_16x16x64_i8 v[26:29], v[162:165], v[210:213], v[26:29]
	v_mfma_i32_16x16x64_i8 v[26:29], v[166:169], v[214:217], v[26:29]
	v_mfma_i32_16x16x64_i8 v[46:49], v[170:173], v[186:189], v[46:49]
	v_mfma_i32_16x16x64_i8 v[46:49], v[174:177], v[190:193], v[46:49]
	v_mfma_i32_16x16x64_i8 v[14:17], v[178:181], v[186:189], v[14:17]
	v_mfma_i32_16x16x64_i8 v[14:17], v[182:185], v[190:193], v[14:17]
	v_mfma_i32_16x16x64_i8 v[42:45], v[170:173], v[194:197], v[42:45]
	v_mfma_i32_16x16x64_i8 v[42:45], v[174:177], v[198:201], v[42:45]
	v_mfma_i32_16x16x64_i8 v[10:13], v[178:181], v[194:197], v[10:13]
	v_mfma_i32_16x16x64_i8 v[10:13], v[182:185], v[198:201], v[10:13]
	v_mfma_i32_16x16x64_i8 v[38:41], v[170:173], v[202:205], v[38:41]
	v_mfma_i32_16x16x64_i8 v[38:41], v[174:177], v[206:209], v[38:41]
	v_mfma_i32_16x16x64_i8 v[6:9], v[178:181], v[202:205], v[6:9]
	v_mfma_i32_16x16x64_i8 v[6:9], v[182:185], v[206:209], v[6:9]
	v_mfma_i32_16x16x64_i8 v[34:37], v[170:173], v[210:213], v[34:37]
	v_mfma_i32_16x16x64_i8 v[34:37], v[174:177], v[214:217], v[34:37]
	v_mfma_i32_16x16x64_i8 v[2:5], v[178:181], v[210:213], v[2:5]
	v_mfma_i32_16x16x64_i8 v[2:5], v[182:185], v[214:217], v[2:5]
	s_barrier
	s_add_i32 s80, s80, 2
	s_add_u32 vcc_hi, vcc_hi, 0x100
	s_addc_u32 s79, s79, 0
	s_cmp_gt_u32 s80, 29
	s_mov_b64 s[4:5], s[6:7]

.Lrlx3_0:
	s_waitcnt lgkmcnt(0)
	s_barrier
	v_mfma_f32_16x16x32_bf16 v[150:153], v[114:117], v[162:165], 0
	v_mfma_f32_16x16x32_bf16 v[150:153], v[118:121], v[166:169], v[150:153]
	v_mfma_f32_16x16x32_bf16 v[146:149], v[126:129], v[162:165], 0
	v_mfma_f32_16x16x32_bf16 v[146:149], v[134:137], v[166:169], v[146:149]
	v_mfma_f32_16x16x32_bf16 v[110:113], v[114:117], v[170:173], 0
	v_mfma_f32_16x16x32_bf16 v[110:113], v[118:121], v[174:177], v[110:113]
	v_mfma_f32_16x16x32_bf16 v[106:109], v[126:129], v[170:173], 0
	v_mfma_f32_16x16x32_bf16 v[106:109], v[134:137], v[174:177], v[106:109]
	v_mfma_f32_16x16x32_bf16 v[94:97], v[114:117], v[178:181], 0
	v_mfma_f32_16x16x32_bf16 v[94:97], v[118:121], v[182:185], v[94:97]
	v_mfma_f32_16x16x32_bf16 v[90:93], v[126:129], v[178:181], 0
	v_mfma_f32_16x16x32_bf16 v[90:93], v[134:137], v[182:185], v[90:93]
	v_mfma_f32_16x16x32_bf16 v[78:81], v[114:117], v[186:189], 0
	v_mfma_f32_16x16x32_bf16 v[78:81], v[118:121], v[190:193], v[78:81]
	v_mfma_f32_16x16x32_bf16 v[74:77], v[126:129], v[186:189], 0
	v_mfma_f32_16x16x32_bf16 v[74:77], v[134:137], v[190:193], v[74:77]
	v_mfma_f32_16x16x32_bf16 v[130:133], v[138:141], v[162:165], 0
	v_mfma_f32_16x16x32_bf16 v[130:133], v[142:145], v[166:169], v[130:133]
	v_mfma_f32_16x16x32_bf16 v[122:125], v[154:157], v[162:165], 0
	v_mfma_f32_16x16x32_bf16 v[122:125], v[158:161], v[166:169], v[122:125]
	v_mfma_f32_16x16x32_bf16 v[102:105], v[138:141], v[170:173], 0
	v_mfma_f32_16x16x32_bf16 v[102:105], v[142:145], v[174:177], v[102:105]
	v_mfma_f32_16x16x32_bf16 v[98:101], v[154:157], v[170:173], 0
	v_mfma_f32_16x16x32_bf16 v[98:101], v[158:161], v[174:177], v[98:101]
	v_mfma_f32_16x16x32_bf16 v[86:89], v[138:141], v[178:181], 0
	v_mfma_f32_16x16x32_bf16 v[86:89], v[142:145], v[182:185], v[86:89]
	v_mfma_f32_16x16x32_bf16 v[82:85], v[154:157], v[178:181], 0
	v_mfma_f32_16x16x32_bf16 v[82:85], v[158:161], v[182:185], v[82:85]
	v_mfma_f32_16x16x32_bf16 v[70:73], v[138:141], v[186:189], 0
	v_mfma_f32_16x16x32_bf16 v[70:73], v[142:145], v[190:193], v[70:73]
	v_mfma_f32_16x16x32_bf16 v[66:69], v[154:157], v[186:189], 0
	v_mfma_f32_16x16x32_bf16 v[66:69], v[158:161], v[190:193], v[66:69]
	s_barrier
	s_add_i32 s18, s42, s16
	v_lshl_add_u64 v[210:211], s[26:27], 0, v[196:197]
	s_mov_b32 m0, s18
	ds_read_b128 v[162:165], v249 offset:16384
	ds_read_b128 v[166:169], v249 offset:17408
	ds_read_b128 v[170:173], v249 offset:18432
	ds_read_b128 v[174:177], v249 offset:19456
	ds_read_b128 v[178:181], v249 offset:20480
	ds_read_b128 v[182:185], v249 offset:21504
	ds_read_b128 v[186:189], v249 offset:22528
	ds_read_b128 v[190:193], v249 offset:23552
	global_load_lds_dwordx4 v[210:211], off
	s_add_i32 m0, s18, 0x2000
	s_add_u32 s18, s26, 0x380000
	v_lshl_add_u64 v[212:213], s[26:27], 0, v[200:201]
	s_addc_u32 s19, s27, 0
	s_add_i32 s67, s43, s16
	global_load_lds_dwordx4 v[212:213], off
	v_lshl_add_u64 v[214:215], s[18:19], 0, v[196:197]
	s_mov_b32 m0, s67
	v_lshl_add_u64 v[216:217], s[28:29], 0, v[198:199]
	global_load_lds_dwordx4 v[214:215], off
	v_lshl_add_u64 v[214:215], s[18:19], 0, v[200:201]
	s_add_i32 m0, s67, 0x2000
	s_nop 0
	global_load_lds_dwordx4 v[214:215], off
	v_lshl_add_u64 v[214:215], s[28:29], 0, v[194:195]
	s_mov_b32 m0, s17
	s_nop 0
	global_load_lds_dwordx4 v[214:215], off
	s_mov_b32 m0, s30
	s_nop 0
	global_load_lds_dwordx4 v[216:217], off
	s_waitcnt vmcnt(24)
	s_cmp_lg_u32 s35, 1
	s_cbranch_scc1 .Lrlx3_1
	s_waitcnt vmcnt(8)
.Lrlx3_1:
	s_waitcnt lgkmcnt(0)
	s_barrier
	v_mfma_f32_16x16x32_bf16 v[62:65], v[114:117], v[162:165], 0
	v_mfma_f32_16x16x32_bf16 v[62:65], v[118:121], v[166:169], v[62:65]
	v_mfma_f32_16x16x32_bf16 v[58:61], v[126:129], v[162:165], 0
	v_mfma_f32_16x16x32_bf16 v[58:61], v[134:137], v[166:169], v[58:61]
	v_mfma_f32_16x16x32_bf16 v[46:49], v[114:117], v[170:173], 0
	v_mfma_f32_16x16x32_bf16 v[46:49], v[118:121], v[174:177], v[46:49]
	v_mfma_f32_16x16x32_bf16 v[42:45], v[126:129], v[170:173], 0
	v_mfma_f32_16x16x32_bf16 v[42:45], v[134:137], v[174:177], v[42:45]
	v_mfma_f32_16x16x32_bf16 v[30:33], v[114:117], v[178:181], 0
	v_mfma_f32_16x16x32_bf16 v[30:33], v[118:121], v[182:185], v[30:33]
	v_mfma_f32_16x16x32_bf16 v[26:29], v[126:129], v[178:181], 0
	v_mfma_f32_16x16x32_bf16 v[26:29], v[134:137], v[182:185], v[26:29]
	v_mfma_f32_16x16x32_bf16 v[14:17], v[114:117], v[186:189], 0
	v_mfma_f32_16x16x32_bf16 v[14:17], v[118:121], v[190:193], v[14:17]
	v_mfma_f32_16x16x32_bf16 v[10:13], v[126:129], v[186:189], 0
	v_mfma_f32_16x16x32_bf16 v[10:13], v[134:137], v[190:193], v[10:13]
	v_mfma_f32_16x16x32_bf16 v[54:57], v[138:141], v[162:165], 0
	v_mfma_f32_16x16x32_bf16 v[54:57], v[142:145], v[166:169], v[54:57]
	v_mfma_f32_16x16x32_bf16 v[50:53], v[154:157], v[162:165], 0
	v_mfma_f32_16x16x32_bf16 v[50:53], v[158:161], v[166:169], v[50:53]
	v_mfma_f32_16x16x32_bf16 v[38:41], v[138:141], v[170:173], 0
	v_mfma_f32_16x16x32_bf16 v[38:41], v[142:145], v[174:177], v[38:41]
	v_mfma_f32_16x16x32_bf16 v[34:37], v[154:157], v[170:173], 0
	v_mfma_f32_16x16x32_bf16 v[34:37], v[158:161], v[174:177], v[34:37]
	v_mfma_f32_16x16x32_bf16 v[22:25], v[138:141], v[178:181], 0
	v_mfma_f32_16x16x32_bf16 v[22:25], v[142:145], v[182:185], v[22:25]
	v_mfma_f32_16x16x32_bf16 v[18:21], v[154:157], v[178:181], 0
	v_mfma_f32_16x16x32_bf16 v[18:21], v[158:161], v[182:185], v[18:21]
	v_mfma_f32_16x16x32_bf16 v[6:9], v[138:141], v[186:189], 0
	v_mfma_f32_16x16x32_bf16 v[6:9], v[142:145], v[190:193], v[6:9]
	v_mfma_f32_16x16x32_bf16 v[2:5], v[154:157], v[186:189], 0
	v_mfma_f32_16x16x32_bf16 v[2:5], v[158:161], v[190:193], v[2:5]
	s_barrier
	s_add_i32 s67, 0, 0x18000
	s_add_i32 s68, 0, 0x1c000
	v_add_u32_e32 v134, s67, v244
	v_add_u32_e32 v158, s68, v244
	ds_read_b128 v[114:117], v134
	ds_read_b128 v[118:121], v134 offset:1024
	ds_read_b128 v[126:129], v134 offset:2048
	ds_read_b128 v[134:137], v134 offset:3072
	ds_read_b128 v[138:141], v158
	ds_read_b128 v[142:145], v158 offset:1024
	ds_read_b128 v[154:157], v158 offset:2048
	ds_read_b128 v[158:161], v158 offset:3072
	s_add_u32 s18, s28, 0x380000
	s_addc_u32 s19, s29, 0
	s_mov_b32 m0, s31
	v_lshl_add_u64 v[218:219], s[18:19], 0, v[194:195]
	ds_read_b128 v[162:165], v249 offset:32768
	ds_read_b128 v[166:169], v249 offset:33792
	ds_read_b128 v[170:173], v249 offset:34816
	ds_read_b128 v[174:177], v249 offset:35840
	ds_read_b128 v[178:181], v249 offset:36864
	ds_read_b128 v[182:185], v249 offset:37888
	ds_read_b128 v[186:189], v249 offset:38912
	ds_read_b128 v[190:193], v249 offset:39936
	global_load_lds_dwordx4 v[218:219], off
	v_lshl_add_u64 v[218:219], s[18:19], 0, v[198:199]
	s_mov_b32 m0, s34
	s_nop 0
	global_load_lds_dwordx4 v[218:219], off
	s_waitcnt vmcnt(8)
	s_waitcnt lgkmcnt(0)
	s_barrier
	v_mfma_f32_16x16x32_bf16 v[150:153], v[114:117], v[162:165], v[150:153]
	v_mfma_f32_16x16x32_bf16 v[150:153], v[118:121], v[166:169], v[150:153]
	v_mfma_f32_16x16x32_bf16 v[146:149], v[126:129], v[162:165], v[146:149]
	v_mfma_f32_16x16x32_bf16 v[146:149], v[134:137], v[166:169], v[146:149]
	v_mfma_f32_16x16x32_bf16 v[110:113], v[114:117], v[170:173], v[110:113]
	v_mfma_f32_16x16x32_bf16 v[110:113], v[118:121], v[174:177], v[110:113]
	v_mfma_f32_16x16x32_bf16 v[106:109], v[126:129], v[170:173], v[106:109]
	v_mfma_f32_16x16x32_bf16 v[106:109], v[134:137], v[174:177], v[106:109]
	v_mfma_f32_16x16x32_bf16 v[94:97], v[114:117], v[178:181], v[94:97]
	v_mfma_f32_16x16x32_bf16 v[94:97], v[118:121], v[182:185], v[94:97]
	v_mfma_f32_16x16x32_bf16 v[90:93], v[126:129], v[178:181], v[90:93]
	v_mfma_f32_16x16x32_bf16 v[90:93], v[134:137], v[182:185], v[90:93]
	v_mfma_f32_16x16x32_bf16 v[78:81], v[114:117], v[186:189], v[78:81]
	v_mfma_f32_16x16x32_bf16 v[78:81], v[118:121], v[190:193], v[78:81]
	v_mfma_f32_16x16x32_bf16 v[74:77], v[126:129], v[186:189], v[74:77]
	v_mfma_f32_16x16x32_bf16 v[74:77], v[134:137], v[190:193], v[74:77]
	v_mfma_f32_16x16x32_bf16 v[130:133], v[138:141], v[162:165], v[130:133]
	v_mfma_f32_16x16x32_bf16 v[130:133], v[142:145], v[166:169], v[130:133]
	v_mfma_f32_16x16x32_bf16 v[122:125], v[154:157], v[162:165], v[122:125]
	v_mfma_f32_16x16x32_bf16 v[122:125], v[158:161], v[166:169], v[122:125]
	v_mfma_f32_16x16x32_bf16 v[102:105], v[138:141], v[170:173], v[102:105]
	v_mfma_f32_16x16x32_bf16 v[102:105], v[142:145], v[174:177], v[102:105]
	v_mfma_f32_16x16x32_bf16 v[98:101], v[154:157], v[170:173], v[98:101]
	v_mfma_f32_16x16x32_bf16 v[98:101], v[158:161], v[174:177], v[98:101]
	v_mfma_f32_16x16x32_bf16 v[86:89], v[138:141], v[178:181], v[86:89]
	v_mfma_f32_16x16x32_bf16 v[86:89], v[142:145], v[182:185], v[86:89]
	v_mfma_f32_16x16x32_bf16 v[82:85], v[154:157], v[178:181], v[82:85]
	v_mfma_f32_16x16x32_bf16 v[82:85], v[158:161], v[182:185], v[82:85]
	v_mfma_f32_16x16x32_bf16 v[70:73], v[138:141], v[186:189], v[70:73]
	v_mfma_f32_16x16x32_bf16 v[70:73], v[142:145], v[190:193], v[70:73]
	v_mfma_f32_16x16x32_bf16 v[66:69], v[154:157], v[186:189], v[66:69]
	v_mfma_f32_16x16x32_bf16 v[66:69], v[158:161], v[190:193], v[66:69]
	s_barrier
	s_add_i32 s18, s67, s16
	v_lshl_add_u64 v[210:211], v[210:211], 0, s[12:13]
	s_mov_b32 m0, s18
	ds_read_b128 v[162:165], v249 offset:49152
	ds_read_b128 v[166:169], v249 offset:50176
	ds_read_b128 v[170:173], v249 offset:51200
	ds_read_b128 v[174:177], v249 offset:52224
	ds_read_b128 v[178:181], v249 offset:53248
	ds_read_b128 v[182:185], v249 offset:54272
	ds_read_b128 v[186:189], v249 offset:55296
	ds_read_b128 v[190:193], v249 offset:56320
	global_load_lds_dwordx4 v[210:211], off
	s_add_i32 m0, s18, 0x2000
	s_add_u32 s18, s26, 0x380080
	v_lshl_add_u64 v[210:211], v[212:213], 0, s[12:13]
	s_addc_u32 s19, s27, 0
	s_add_i32 s26, s68, s16
	global_load_lds_dwordx4 v[210:211], off
	v_lshl_add_u64 v[210:211], s[18:19], 0, v[196:197]
	s_mov_b32 m0, s26
	s_nop 0
	global_load_lds_dwordx4 v[210:211], off
	v_lshl_add_u64 v[210:211], s[18:19], 0, v[200:201]
	s_add_i32 m0, s26, 0x2000
	s_nop 0
	global_load_lds_dwordx4 v[210:211], off
	v_lshl_add_u64 v[210:211], v[214:215], 0, s[12:13]
	s_mov_b32 m0, s38
	s_nop 0
	global_load_lds_dwordx4 v[210:211], off
	v_lshl_add_u64 v[210:211], v[216:217], 0, s[12:13]
	s_mov_b32 m0, s39
	s_nop 0
	global_load_lds_dwordx4 v[210:211], off
	s_waitcnt vmcnt(8)
	s_waitcnt lgkmcnt(0)
	s_barrier
	v_mfma_f32_16x16x32_bf16 v[62:65], v[114:117], v[162:165], v[62:65]
	v_mfma_f32_16x16x32_bf16 v[62:65], v[118:121], v[166:169], v[62:65]
	v_mfma_f32_16x16x32_bf16 v[58:61], v[126:129], v[162:165], v[58:61]
	v_mfma_f32_16x16x32_bf16 v[58:61], v[134:137], v[166:169], v[58:61]
	v_mfma_f32_16x16x32_bf16 v[46:49], v[114:117], v[170:173], v[46:49]
	v_mfma_f32_16x16x32_bf16 v[46:49], v[118:121], v[174:177], v[46:49]
	v_mfma_f32_16x16x32_bf16 v[42:45], v[126:129], v[170:173], v[42:45]
	v_mfma_f32_16x16x32_bf16 v[42:45], v[134:137], v[174:177], v[42:45]
	v_mfma_f32_16x16x32_bf16 v[30:33], v[114:117], v[178:181], v[30:33]
	v_mfma_f32_16x16x32_bf16 v[30:33], v[118:121], v[182:185], v[30:33]
	v_mfma_f32_16x16x32_bf16 v[26:29], v[126:129], v[178:181], v[26:29]
	v_mfma_f32_16x16x32_bf16 v[26:29], v[134:137], v[182:185], v[26:29]
	v_mfma_f32_16x16x32_bf16 v[14:17], v[114:117], v[186:189], v[14:17]
	v_mfma_f32_16x16x32_bf16 v[14:17], v[118:121], v[190:193], v[14:17]
	v_mfma_f32_16x16x32_bf16 v[10:13], v[126:129], v[186:189], v[10:13]
	v_mfma_f32_16x16x32_bf16 v[10:13], v[134:137], v[190:193], v[10:13]
	v_mfma_f32_16x16x32_bf16 v[54:57], v[138:141], v[162:165], v[54:57]
	v_mfma_f32_16x16x32_bf16 v[54:57], v[142:145], v[166:169], v[54:57]
	v_mfma_f32_16x16x32_bf16 v[50:53], v[154:157], v[162:165], v[50:53]
	v_mfma_f32_16x16x32_bf16 v[50:53], v[158:161], v[166:169], v[50:53]
	v_mfma_f32_16x16x32_bf16 v[38:41], v[138:141], v[170:173], v[38:41]
	v_mfma_f32_16x16x32_bf16 v[38:41], v[142:145], v[174:177], v[38:41]
	v_mfma_f32_16x16x32_bf16 v[34:37], v[154:157], v[170:173], v[34:37]
	v_mfma_f32_16x16x32_bf16 v[34:37], v[158:161], v[174:177], v[34:37]
	v_mfma_f32_16x16x32_bf16 v[22:25], v[138:141], v[178:181], v[22:25]
	v_mfma_f32_16x16x32_bf16 v[22:25], v[142:145], v[182:185], v[22:25]
	v_mfma_f32_16x16x32_bf16 v[18:21], v[154:157], v[178:181], v[18:21]
	v_mfma_f32_16x16x32_bf16 v[18:21], v[158:161], v[182:185], v[18:21]
	v_mfma_f32_16x16x32_bf16 v[6:9], v[138:141], v[186:189], v[6:9]
	v_mfma_f32_16x16x32_bf16 v[6:9], v[142:145], v[190:193], v[6:9]
	v_mfma_f32_16x16x32_bf16 v[2:5], v[154:157], v[186:189], v[2:5]
	v_mfma_f32_16x16x32_bf16 v[2:5], v[158:161], v[190:193], v[2:5]
	s_barrier
	s_add_i32 s66, s66, 2
	s_add_u32 s64, s64, 0x100
	s_addc_u32 s65, s65, 0
	s_cmpk_gt_u32 s66, 0xdd
	s_mov_b64 s[18:19], s[4:5]

.Lrlx4_0:
	s_waitcnt lgkmcnt(0)
	s_barrier
	v_mfma_f32_16x16x32_bf16 v[138:141], v[30:33], v[180:183], 0
	v_mfma_f32_16x16x32_bf16 v[138:141], v[38:41], v[184:187], v[138:141]
	v_mfma_f32_16x16x32_bf16 v[142:145], v[42:45], v[180:183], 0
	v_mfma_f32_16x16x32_bf16 v[142:145], v[50:53], v[184:187], v[142:145]
	v_mfma_f32_16x16x32_bf16 v[122:125], v[30:33], v[188:191], 0
	v_mfma_f32_16x16x32_bf16 v[122:125], v[38:41], v[192:195], v[122:125]
	v_mfma_f32_16x16x32_bf16 v[126:129], v[42:45], v[188:191], 0
	v_mfma_f32_16x16x32_bf16 v[126:129], v[50:53], v[192:195], v[126:129]
	v_mfma_f32_16x16x32_bf16 v[106:109], v[30:33], v[206:209], 0
	v_mfma_f32_16x16x32_bf16 v[106:109], v[38:41], v[210:213], v[106:109]
	v_mfma_f32_16x16x32_bf16 v[110:113], v[42:45], v[206:209], 0
	v_mfma_f32_16x16x32_bf16 v[110:113], v[50:53], v[210:213], v[110:113]
	v_mfma_f32_16x16x32_bf16 v[90:93], v[30:33], v[214:217], 0
	v_mfma_f32_16x16x32_bf16 v[90:93], v[38:41], v[218:221], v[90:93]
	v_mfma_f32_16x16x32_bf16 v[94:97], v[42:45], v[214:217], 0
	v_mfma_f32_16x16x32_bf16 v[94:97], v[50:53], v[218:221], v[94:97]
	v_mfma_f32_16x16x32_bf16 v[130:133], v[164:167], v[180:183], 0
	v_mfma_f32_16x16x32_bf16 v[130:133], v[168:171], v[184:187], v[130:133]
	v_mfma_f32_16x16x32_bf16 v[134:137], v[172:175], v[180:183], 0
	v_mfma_f32_16x16x32_bf16 v[134:137], v[176:179], v[184:187], v[134:137]
	v_mfma_f32_16x16x32_bf16 v[114:117], v[164:167], v[188:191], 0
	v_mfma_f32_16x16x32_bf16 v[114:117], v[168:171], v[192:195], v[114:117]
	v_mfma_f32_16x16x32_bf16 v[118:121], v[172:175], v[188:191], 0
	v_mfma_f32_16x16x32_bf16 v[118:121], v[176:179], v[192:195], v[118:121]
	v_mfma_f32_16x16x32_bf16 v[98:101], v[164:167], v[206:209], 0
	v_mfma_f32_16x16x32_bf16 v[98:101], v[168:171], v[210:213], v[98:101]
	v_mfma_f32_16x16x32_bf16 v[102:105], v[172:175], v[206:209], 0
	v_mfma_f32_16x16x32_bf16 v[102:105], v[176:179], v[210:213], v[102:105]
	v_mfma_f32_16x16x32_bf16 v[82:85], v[164:167], v[214:217], 0
	v_mfma_f32_16x16x32_bf16 v[82:85], v[168:171], v[218:221], v[82:85]
	v_mfma_f32_16x16x32_bf16 v[86:89], v[172:175], v[214:217], 0
	v_mfma_f32_16x16x32_bf16 v[86:89], v[176:179], v[218:221], v[86:89]
	s_barrier
	s_add_i32 s63, s77, s37
	v_lshl_add_u64 v[222:223], s[18:19], 0, v[148:149]
	s_mov_b32 m0, s63
	ds_read_b128 v[180:183], v202 offset:16384
	ds_read_b128 v[184:187], v202 offset:17408
	ds_read_b128 v[188:191], v202 offset:18432
	ds_read_b128 v[192:195], v202 offset:19456
	ds_read_b128 v[206:209], v202 offset:20480
	ds_read_b128 v[210:213], v202 offset:21504
	ds_read_b128 v[214:217], v202 offset:22528
	ds_read_b128 v[218:221], v202 offset:23552
	global_load_lds_dwordx4 v[222:223], off
	s_add_i32 m0, s63, 0x2000
	s_add_u32 s82, s18, 0x100000
	v_lshl_add_u64 v[224:225], s[18:19], 0, v[152:153]
	s_addc_u32 s83, s19, 0
	s_add_i32 s63, s78, s37
	global_load_lds_dwordx4 v[224:225], off
	v_lshl_add_u64 v[226:227], s[82:83], 0, v[148:149]
	s_mov_b32 m0, s63
	v_lshl_add_u64 v[228:229], s[68:69], 0, v[150:151]
	global_load_lds_dwordx4 v[226:227], off
	v_lshl_add_u64 v[226:227], s[82:83], 0, v[152:153]
	s_add_i32 m0, s63, 0x2000
	s_nop 0
	global_load_lds_dwordx4 v[226:227], off
	v_lshl_add_u64 v[226:227], s[68:69], 0, v[146:147]
	s_mov_b32 m0, s39
	s_nop 0
	global_load_lds_dwordx4 v[226:227], off
	s_mov_b32 m0, s41
	s_nop 0
	global_load_lds_dwordx4 v[228:229], off
	s_waitcnt vmcnt(24)
	s_cmp_lg_u32 s70, 1
	s_cbranch_scc1 .Lrlx4_1
	s_waitcnt vmcnt(8)
.Lrlx4_1:
	s_waitcnt lgkmcnt(0)
	s_barrier
	v_mfma_f32_16x16x32_bf16 v[74:77], v[30:33], v[180:183], 0
	v_mfma_f32_16x16x32_bf16 v[74:77], v[38:41], v[184:187], v[74:77]
	v_mfma_f32_16x16x32_bf16 v[78:81], v[42:45], v[180:183], 0
	v_mfma_f32_16x16x32_bf16 v[78:81], v[50:53], v[184:187], v[78:81]
	v_mfma_f32_16x16x32_bf16 v[58:61], v[30:33], v[188:191], 0
	v_mfma_f32_16x16x32_bf16 v[58:61], v[38:41], v[192:195], v[58:61]
	v_mfma_f32_16x16x32_bf16 v[62:65], v[42:45], v[188:191], 0
	v_mfma_f32_16x16x32_bf16 v[62:65], v[50:53], v[192:195], v[62:65]
	v_mfma_f32_16x16x32_bf16 v[26:29], v[30:33], v[206:209], 0
	v_mfma_f32_16x16x32_bf16 v[26:29], v[38:41], v[210:213], v[26:29]
	v_mfma_f32_16x16x32_bf16 v[34:37], v[42:45], v[206:209], 0
	v_mfma_f32_16x16x32_bf16 v[34:37], v[50:53], v[210:213], v[34:37]
	v_mfma_f32_16x16x32_bf16 v[10:13], v[30:33], v[214:217], 0
	v_mfma_f32_16x16x32_bf16 v[10:13], v[38:41], v[218:221], v[10:13]
	v_mfma_f32_16x16x32_bf16 v[14:17], v[42:45], v[214:217], 0
	v_mfma_f32_16x16x32_bf16 v[14:17], v[50:53], v[218:221], v[14:17]
	v_mfma_f32_16x16x32_bf16 v[18:21], v[164:167], v[206:209], 0
	v_mfma_f32_16x16x32_bf16 v[18:21], v[168:171], v[210:213], v[18:21]
	v_mfma_f32_16x16x32_bf16 v[22:25], v[172:175], v[206:209], 0
	v_mfma_f32_16x16x32_bf16 v[22:25], v[176:179], v[210:213], v[22:25]
	v_mfma_f32_16x16x32_bf16 v[2:5], v[164:167], v[214:217], 0
	v_mfma_f32_16x16x32_bf16 v[2:5], v[168:171], v[218:221], v[2:5]
	v_mfma_f32_16x16x32_bf16 v[6:9], v[172:175], v[214:217], 0
	v_mfma_f32_16x16x32_bf16 v[6:9], v[176:179], v[218:221], v[6:9]
	v_mfma_f32_16x16x32_bf16 v[30:33], v[164:167], v[180:183], 0
	v_mfma_f32_16x16x32_bf16 v[30:33], v[168:171], v[184:187], v[30:33]
	v_mfma_f32_16x16x32_bf16 v[38:41], v[172:175], v[180:183], 0
	v_mfma_f32_16x16x32_bf16 v[38:41], v[176:179], v[184:187], v[38:41]
	v_mfma_f32_16x16x32_bf16 v[42:45], v[164:167], v[188:191], 0
	v_mfma_f32_16x16x32_bf16 v[42:45], v[168:171], v[192:195], v[42:45]
	v_mfma_f32_16x16x32_bf16 v[46:49], v[172:175], v[188:191], 0
	v_mfma_f32_16x16x32_bf16 v[50:53], v[176:179], v[192:195], v[46:49]
	s_barrier
	s_add_i32 s63, 0, 0x18000
	s_add_i32 s82, 0, 0x1c000
	v_add_u32_e32 v70, s63, v196
	v_add_u32_e32 v155, s82, v196
	ds_read_b128 v[46:49], v70
	ds_read_b128 v[54:57], v70 offset:1024
	ds_read_b128 v[66:69], v70 offset:2048
	ds_read_b128 v[70:73], v70 offset:3072
	ds_read_b128 v[164:167], v155
	ds_read_b128 v[168:171], v155 offset:1024
	ds_read_b128 v[172:175], v155 offset:2048
	ds_read_b128 v[176:179], v155 offset:3072
	s_add_u32 s68, s68, 0x100000
	s_addc_u32 s69, s69, 0
	s_mov_b32 m0, s43
	v_lshl_add_u64 v[230:231], s[68:69], 0, v[146:147]
	ds_read_b128 v[180:183], v202 offset:32768
	ds_read_b128 v[184:187], v202 offset:33792
	ds_read_b128 v[188:191], v202 offset:34816
	ds_read_b128 v[192:195], v202 offset:35840
	ds_read_b128 v[206:209], v202 offset:36864
	ds_read_b128 v[210:213], v202 offset:37888
	ds_read_b128 v[214:217], v202 offset:38912
	ds_read_b128 v[218:221], v202 offset:39936
	global_load_lds_dwordx4 v[230:231], off
	v_lshl_add_u64 v[230:231], s[68:69], 0, v[150:151]
	s_mov_b32 m0, s57
	s_nop 0
	global_load_lds_dwordx4 v[230:231], off
	s_waitcnt vmcnt(8)
	s_waitcnt lgkmcnt(0)
	s_barrier
	v_mfma_f32_16x16x32_bf16 v[138:141], v[46:49], v[180:183], v[138:141]
	v_mfma_f32_16x16x32_bf16 v[138:141], v[54:57], v[184:187], v[138:141]
	v_mfma_f32_16x16x32_bf16 v[142:145], v[66:69], v[180:183], v[142:145]
	v_mfma_f32_16x16x32_bf16 v[142:145], v[70:73], v[184:187], v[142:145]
	v_mfma_f32_16x16x32_bf16 v[122:125], v[46:49], v[188:191], v[122:125]
	v_mfma_f32_16x16x32_bf16 v[122:125], v[54:57], v[192:195], v[122:125]
	v_mfma_f32_16x16x32_bf16 v[126:129], v[66:69], v[188:191], v[126:129]
	v_mfma_f32_16x16x32_bf16 v[126:129], v[70:73], v[192:195], v[126:129]
	v_mfma_f32_16x16x32_bf16 v[106:109], v[46:49], v[206:209], v[106:109]
	v_mfma_f32_16x16x32_bf16 v[106:109], v[54:57], v[210:213], v[106:109]
	v_mfma_f32_16x16x32_bf16 v[110:113], v[66:69], v[206:209], v[110:113]
	v_mfma_f32_16x16x32_bf16 v[110:113], v[70:73], v[210:213], v[110:113]
	v_mfma_f32_16x16x32_bf16 v[90:93], v[46:49], v[214:217], v[90:93]
	v_mfma_f32_16x16x32_bf16 v[90:93], v[54:57], v[218:221], v[90:93]
	v_mfma_f32_16x16x32_bf16 v[94:97], v[66:69], v[214:217], v[94:97]
	v_mfma_f32_16x16x32_bf16 v[94:97], v[70:73], v[218:221], v[94:97]
	v_mfma_f32_16x16x32_bf16 v[130:133], v[164:167], v[180:183], v[130:133]
	v_mfma_f32_16x16x32_bf16 v[130:133], v[168:171], v[184:187], v[130:133]
	v_mfma_f32_16x16x32_bf16 v[134:137], v[172:175], v[180:183], v[134:137]
	v_mfma_f32_16x16x32_bf16 v[134:137], v[176:179], v[184:187], v[134:137]
	v_mfma_f32_16x16x32_bf16 v[114:117], v[164:167], v[188:191], v[114:117]
	v_mfma_f32_16x16x32_bf16 v[114:117], v[168:171], v[192:195], v[114:117]
	v_mfma_f32_16x16x32_bf16 v[118:121], v[172:175], v[188:191], v[118:121]
	v_mfma_f32_16x16x32_bf16 v[118:121], v[176:179], v[192:195], v[118:121]
	v_mfma_f32_16x16x32_bf16 v[98:101], v[164:167], v[206:209], v[98:101]
	v_mfma_f32_16x16x32_bf16 v[98:101], v[168:171], v[210:213], v[98:101]
	v_mfma_f32_16x16x32_bf16 v[102:105], v[172:175], v[206:209], v[102:105]
	v_mfma_f32_16x16x32_bf16 v[102:105], v[176:179], v[210:213], v[102:105]
	v_mfma_f32_16x16x32_bf16 v[82:85], v[164:167], v[214:217], v[82:85]
	v_mfma_f32_16x16x32_bf16 v[82:85], v[168:171], v[218:221], v[82:85]
	v_mfma_f32_16x16x32_bf16 v[86:89], v[172:175], v[214:217], v[86:89]
	v_mfma_f32_16x16x32_bf16 v[86:89], v[176:179], v[218:221], v[86:89]
	s_barrier
	s_add_i32 s63, s63, s37
	v_lshl_add_u64 v[222:223], v[222:223], 0, s[26:27]
	s_mov_b32 m0, s63
	ds_read_b128 v[180:183], v202 offset:49152
	ds_read_b128 v[184:187], v202 offset:50176
	ds_read_b128 v[188:191], v202 offset:51200
	ds_read_b128 v[192:195], v202 offset:52224
	ds_read_b128 v[206:209], v202 offset:53248
	ds_read_b128 v[210:213], v202 offset:54272
	ds_read_b128 v[214:217], v202 offset:55296
	ds_read_b128 v[218:221], v202 offset:56320
	global_load_lds_dwordx4 v[222:223], off
	s_add_i32 m0, s63, 0x2000
	s_add_u32 s18, s18, 0x100080
	v_lshl_add_u64 v[222:223], v[224:225], 0, s[26:27]
	s_addc_u32 s19, s19, 0
	s_add_i32 s63, s82, s37
	global_load_lds_dwordx4 v[222:223], off
	v_lshl_add_u64 v[222:223], s[18:19], 0, v[148:149]
	s_mov_b32 m0, s63
	s_nop 0
	global_load_lds_dwordx4 v[222:223], off
	v_lshl_add_u64 v[222:223], s[18:19], 0, v[152:153]
	s_add_i32 m0, s63, 0x2000
	s_nop 0
	global_load_lds_dwordx4 v[222:223], off
	v_lshl_add_u64 v[222:223], v[226:227], 0, s[26:27]
	s_mov_b32 m0, s71
	s_nop 0
	global_load_lds_dwordx4 v[222:223], off
	v_lshl_add_u64 v[222:223], v[228:229], 0, s[26:27]
	s_mov_b32 m0, s72
	s_nop 0
	global_load_lds_dwordx4 v[222:223], off
	s_waitcnt vmcnt(8)
	s_waitcnt lgkmcnt(0)
	s_barrier
	v_mfma_f32_16x16x32_bf16 v[74:77], v[46:49], v[180:183], v[74:77]
	v_mfma_f32_16x16x32_bf16 v[74:77], v[54:57], v[184:187], v[74:77]
	v_mfma_f32_16x16x32_bf16 v[78:81], v[66:69], v[180:183], v[78:81]
	v_mfma_f32_16x16x32_bf16 v[78:81], v[70:73], v[184:187], v[78:81]
	v_mfma_f32_16x16x32_bf16 v[58:61], v[46:49], v[188:191], v[58:61]
	v_mfma_f32_16x16x32_bf16 v[58:61], v[54:57], v[192:195], v[58:61]
	v_mfma_f32_16x16x32_bf16 v[62:65], v[66:69], v[188:191], v[62:65]
	v_mfma_f32_16x16x32_bf16 v[62:65], v[70:73], v[192:195], v[62:65]
	v_mfma_f32_16x16x32_bf16 v[26:29], v[46:49], v[206:209], v[26:29]
	v_mfma_f32_16x16x32_bf16 v[26:29], v[54:57], v[210:213], v[26:29]
	v_mfma_f32_16x16x32_bf16 v[34:37], v[66:69], v[206:209], v[34:37]
	v_mfma_f32_16x16x32_bf16 v[34:37], v[70:73], v[210:213], v[34:37]
	v_mfma_f32_16x16x32_bf16 v[10:13], v[46:49], v[214:217], v[10:13]
	v_mfma_f32_16x16x32_bf16 v[10:13], v[54:57], v[218:221], v[10:13]
	v_mfma_f32_16x16x32_bf16 v[14:17], v[66:69], v[214:217], v[14:17]
	v_mfma_f32_16x16x32_bf16 v[14:17], v[70:73], v[218:221], v[14:17]
	v_mfma_f32_16x16x32_bf16 v[30:33], v[164:167], v[180:183], v[30:33]
	v_mfma_f32_16x16x32_bf16 v[66:69], v[168:171], v[184:187], v[30:33]
	v_mfma_f32_16x16x32_bf16 v[30:33], v[172:175], v[180:183], v[38:41]
	v_mfma_f32_16x16x32_bf16 v[70:73], v[176:179], v[184:187], v[30:33]
	v_mfma_f32_16x16x32_bf16 v[30:33], v[164:167], v[188:191], v[42:45]
	v_mfma_f32_16x16x32_bf16 v[46:49], v[168:171], v[192:195], v[30:33]
	v_mfma_f32_16x16x32_bf16 v[30:33], v[172:175], v[188:191], v[50:53]
	v_mfma_f32_16x16x32_bf16 v[54:57], v[176:179], v[192:195], v[30:33]
	v_mfma_f32_16x16x32_bf16 v[18:21], v[164:167], v[206:209], v[18:21]
	v_mfma_f32_16x16x32_bf16 v[18:21], v[168:171], v[210:213], v[18:21]
	v_mfma_f32_16x16x32_bf16 v[22:25], v[172:175], v[206:209], v[22:25]
	v_mfma_f32_16x16x32_bf16 v[22:25], v[176:179], v[210:213], v[22:25]
	v_mfma_f32_16x16x32_bf16 v[2:5], v[164:167], v[214:217], v[2:5]
	v_mfma_f32_16x16x32_bf16 v[2:5], v[168:171], v[218:221], v[2:5]
	v_mfma_f32_16x16x32_bf16 v[6:9], v[172:175], v[214:217], v[6:9]
	v_mfma_f32_16x16x32_bf16 v[6:9], v[176:179], v[218:221], v[6:9]
	s_barrier
	s_add_i32 s61, s61, 2
	s_add_u32 s10, s10, 0x100
	s_addc_u32 s11, s11, 0
	s_add_u32 s16, s16, 0x100
	s_addc_u32 s17, s17, 0
	s_cmp_gt_u32 s61, 61

.Lrlx5_0:
	s_waitcnt lgkmcnt(0)
	s_barrier
	v_mfma_f32_16x16x32_bf16 v[126:129], v[130:133], v[162:165], 0
	v_mfma_f32_16x16x32_bf16 v[126:129], v[134:137], v[166:169], v[126:129]
	v_mfma_f32_16x16x32_bf16 v[122:125], v[138:141], v[162:165], 0
	v_mfma_f32_16x16x32_bf16 v[122:125], v[142:145], v[166:169], v[122:125]
	v_mfma_f32_16x16x32_bf16 v[110:113], v[130:133], v[186:189], 0
	v_mfma_f32_16x16x32_bf16 v[110:113], v[134:137], v[190:193], v[110:113]
	v_mfma_f32_16x16x32_bf16 v[106:109], v[138:141], v[186:189], 0
	v_mfma_f32_16x16x32_bf16 v[106:109], v[142:145], v[190:193], v[106:109]
	v_mfma_f32_16x16x32_bf16 v[94:97], v[130:133], v[194:197], 0
	v_mfma_f32_16x16x32_bf16 v[94:97], v[134:137], v[198:201], v[94:97]
	v_mfma_f32_16x16x32_bf16 v[90:93], v[138:141], v[194:197], 0
	v_mfma_f32_16x16x32_bf16 v[90:93], v[142:145], v[198:201], v[90:93]
	v_mfma_f32_16x16x32_bf16 v[78:81], v[130:133], v[202:205], 0
	v_mfma_f32_16x16x32_bf16 v[78:81], v[134:137], v[206:209], v[78:81]
	v_mfma_f32_16x16x32_bf16 v[74:77], v[138:141], v[202:205], 0
	v_mfma_f32_16x16x32_bf16 v[74:77], v[142:145], v[206:209], v[74:77]
	v_mfma_f32_16x16x32_bf16 v[118:121], v[146:149], v[162:165], 0
	v_mfma_f32_16x16x32_bf16 v[118:121], v[150:153], v[166:169], v[118:121]
	v_mfma_f32_16x16x32_bf16 v[114:117], v[154:157], v[162:165], 0
	v_mfma_f32_16x16x32_bf16 v[114:117], v[158:161], v[166:169], v[114:117]
	v_mfma_f32_16x16x32_bf16 v[102:105], v[146:149], v[186:189], 0
	v_mfma_f32_16x16x32_bf16 v[102:105], v[150:153], v[190:193], v[102:105]
	v_mfma_f32_16x16x32_bf16 v[98:101], v[154:157], v[186:189], 0
	v_mfma_f32_16x16x32_bf16 v[98:101], v[158:161], v[190:193], v[98:101]
	v_mfma_f32_16x16x32_bf16 v[86:89], v[146:149], v[194:197], 0
	v_mfma_f32_16x16x32_bf16 v[86:89], v[150:153], v[198:201], v[86:89]
	v_mfma_f32_16x16x32_bf16 v[82:85], v[154:157], v[194:197], 0
	v_mfma_f32_16x16x32_bf16 v[82:85], v[158:161], v[198:201], v[82:85]
	v_mfma_f32_16x16x32_bf16 v[70:73], v[146:149], v[202:205], 0
	v_mfma_f32_16x16x32_bf16 v[70:73], v[150:153], v[206:209], v[70:73]
	v_mfma_f32_16x16x32_bf16 v[66:69], v[154:157], v[202:205], 0
	v_mfma_f32_16x16x32_bf16 v[66:69], v[158:161], v[206:209], v[66:69]
	s_barrier
	s_add_i32 s76, s57, s17
	v_lshl_add_u64 v[216:217], s[40:41], 0, v[172:173]
	s_mov_b32 m0, s76
	ds_read_b128 v[162:165], v214 offset:16384
	ds_read_b128 v[166:169], v214 offset:17408
	ds_read_b128 v[186:189], v214 offset:18432
	ds_read_b128 v[190:193], v214 offset:19456
	ds_read_b128 v[194:197], v214 offset:20480
	ds_read_b128 v[198:201], v214 offset:21504
	ds_read_b128 v[202:205], v214 offset:22528
	ds_read_b128 v[206:209], v214 offset:23552
	global_load_lds_dwordx4 v[216:217], off
	s_add_i32 m0, s76, 0x2000
	s_add_u32 s76, s40, 0x100000
	v_lshl_add_u64 v[218:219], s[40:41], 0, v[176:177]
	s_addc_u32 s77, s41, 0
	s_add_i32 s78, s60, s17
	global_load_lds_dwordx4 v[218:219], off
	v_lshl_add_u64 v[220:221], s[76:77], 0, v[172:173]
	s_mov_b32 m0, s78
	v_lshl_add_u64 v[222:223], s[42:43], 0, v[174:175]
	global_load_lds_dwordx4 v[220:221], off
	v_lshl_add_u64 v[220:221], s[76:77], 0, v[176:177]
	s_add_i32 m0, s78, 0x2000
	s_nop 0
	global_load_lds_dwordx4 v[220:221], off
	v_lshl_add_u64 v[220:221], s[42:43], 0, v[170:171]
	s_mov_b32 m0, s19
	s_nop 0
	global_load_lds_dwordx4 v[220:221], off
	s_mov_b32 m0, s44
	s_nop 0
	global_load_lds_dwordx4 v[222:223], off
	s_waitcnt vmcnt(24)
	s_cmp_lg_u32 s47, 1
	s_cbranch_scc1 .Lrlx5_1
	s_waitcnt vmcnt(8)
.Lrlx5_1:
	s_waitcnt lgkmcnt(0)
	s_barrier
	v_mfma_f32_16x16x32_bf16 v[62:65], v[130:133], v[162:165], 0
	v_mfma_f32_16x16x32_bf16 v[62:65], v[134:137], v[166:169], v[62:65]
	v_mfma_f32_16x16x32_bf16 v[58:61], v[138:141], v[162:165], 0
	v_mfma_f32_16x16x32_bf16 v[58:61], v[142:145], v[166:169], v[58:61]
	v_mfma_f32_16x16x32_bf16 v[46:49], v[130:133], v[186:189], 0
	v_mfma_f32_16x16x32_bf16 v[46:49], v[134:137], v[190:193], v[46:49]
	v_mfma_f32_16x16x32_bf16 v[42:45], v[138:141], v[186:189], 0
	v_mfma_f32_16x16x32_bf16 v[42:45], v[142:145], v[190:193], v[42:45]
	v_mfma_f32_16x16x32_bf16 v[30:33], v[130:133], v[194:197], 0
	v_mfma_f32_16x16x32_bf16 v[30:33], v[134:137], v[198:201], v[30:33]
	v_mfma_f32_16x16x32_bf16 v[26:29], v[138:141], v[194:197], 0
	v_mfma_f32_16x16x32_bf16 v[26:29], v[142:145], v[198:201], v[26:29]
	v_mfma_f32_16x16x32_bf16 v[14:17], v[130:133], v[202:205], 0
	v_mfma_f32_16x16x32_bf16 v[14:17], v[134:137], v[206:209], v[14:17]
	v_mfma_f32_16x16x32_bf16 v[10:13], v[138:141], v[202:205], 0
	v_mfma_f32_16x16x32_bf16 v[10:13], v[142:145], v[206:209], v[10:13]
	v_mfma_f32_16x16x32_bf16 v[54:57], v[146:149], v[162:165], 0
	v_mfma_f32_16x16x32_bf16 v[54:57], v[150:153], v[166:169], v[54:57]
	v_mfma_f32_16x16x32_bf16 v[50:53], v[154:157], v[162:165], 0
	v_mfma_f32_16x16x32_bf16 v[50:53], v[158:161], v[166:169], v[50:53]
	v_mfma_f32_16x16x32_bf16 v[38:41], v[146:149], v[186:189], 0
	v_mfma_f32_16x16x32_bf16 v[38:41], v[150:153], v[190:193], v[38:41]
	v_mfma_f32_16x16x32_bf16 v[34:37], v[154:157], v[186:189], 0
	v_mfma_f32_16x16x32_bf16 v[34:37], v[158:161], v[190:193], v[34:37]
	v_mfma_f32_16x16x32_bf16 v[22:25], v[146:149], v[194:197], 0
	v_mfma_f32_16x16x32_bf16 v[22:25], v[150:153], v[198:201], v[22:25]
	v_mfma_f32_16x16x32_bf16 v[18:21], v[154:157], v[194:197], 0
	v_mfma_f32_16x16x32_bf16 v[18:21], v[158:161], v[198:201], v[18:21]
	v_mfma_f32_16x16x32_bf16 v[6:9], v[146:149], v[202:205], 0
	v_mfma_f32_16x16x32_bf16 v[6:9], v[150:153], v[206:209], v[6:9]
	v_mfma_f32_16x16x32_bf16 v[2:5], v[154:157], v[202:205], 0
	v_mfma_f32_16x16x32_bf16 v[2:5], v[158:161], v[206:209], v[2:5]
	s_barrier
	s_add_i32 s76, 0, 0x18000
	s_add_i32 s77, 0, 0x1c000
	v_add_u32_e32 v142, s76, v211
	v_add_u32_e32 v158, s77, v211
	ds_read_b128 v[130:133], v142
	ds_read_b128 v[134:137], v142 offset:1024
	ds_read_b128 v[138:141], v142 offset:2048
	ds_read_b128 v[142:145], v142 offset:3072
	ds_read_b128 v[146:149], v158
	ds_read_b128 v[150:153], v158 offset:1024
	ds_read_b128 v[154:157], v158 offset:2048
	ds_read_b128 v[158:161], v158 offset:3072
	s_add_u32 s42, s42, 0x100000
	s_addc_u32 s43, s43, 0
	s_mov_b32 m0, s45
	v_lshl_add_u64 v[224:225], s[42:43], 0, v[170:171]
	ds_read_b128 v[162:165], v214 offset:32768
	ds_read_b128 v[166:169], v214 offset:33792
	ds_read_b128 v[186:189], v214 offset:34816
	ds_read_b128 v[190:193], v214 offset:35840
	ds_read_b128 v[194:197], v214 offset:36864
	ds_read_b128 v[198:201], v214 offset:37888
	ds_read_b128 v[202:205], v214 offset:38912
	ds_read_b128 v[206:209], v214 offset:39936
	global_load_lds_dwordx4 v[224:225], off
	v_lshl_add_u64 v[224:225], s[42:43], 0, v[174:175]
	s_mov_b32 m0, s46
	s_nop 0
	global_load_lds_dwordx4 v[224:225], off
	s_waitcnt vmcnt(8)
	s_waitcnt lgkmcnt(0)
	s_barrier
	v_mfma_f32_16x16x32_bf16 v[126:129], v[130:133], v[162:165], v[126:129]
	v_mfma_f32_16x16x32_bf16 v[126:129], v[134:137], v[166:169], v[126:129]
	v_mfma_f32_16x16x32_bf16 v[122:125], v[138:141], v[162:165], v[122:125]
	v_mfma_f32_16x16x32_bf16 v[122:125], v[142:145], v[166:169], v[122:125]
	v_mfma_f32_16x16x32_bf16 v[110:113], v[130:133], v[186:189], v[110:113]
	v_mfma_f32_16x16x32_bf16 v[110:113], v[134:137], v[190:193], v[110:113]
	v_mfma_f32_16x16x32_bf16 v[106:109], v[138:141], v[186:189], v[106:109]
	v_mfma_f32_16x16x32_bf16 v[106:109], v[142:145], v[190:193], v[106:109]
	v_mfma_f32_16x16x32_bf16 v[94:97], v[130:133], v[194:197], v[94:97]
	v_mfma_f32_16x16x32_bf16 v[94:97], v[134:137], v[198:201], v[94:97]
	v_mfma_f32_16x16x32_bf16 v[90:93], v[138:141], v[194:197], v[90:93]
	v_mfma_f32_16x16x32_bf16 v[90:93], v[142:145], v[198:201], v[90:93]
	v_mfma_f32_16x16x32_bf16 v[78:81], v[130:133], v[202:205], v[78:81]
	v_mfma_f32_16x16x32_bf16 v[78:81], v[134:137], v[206:209], v[78:81]
	v_mfma_f32_16x16x32_bf16 v[74:77], v[138:141], v[202:205], v[74:77]
	v_mfma_f32_16x16x32_bf16 v[74:77], v[142:145], v[206:209], v[74:77]
	v_mfma_f32_16x16x32_bf16 v[118:121], v[146:149], v[162:165], v[118:121]
	v_mfma_f32_16x16x32_bf16 v[118:121], v[150:153], v[166:169], v[118:121]
	v_mfma_f32_16x16x32_bf16 v[114:117], v[154:157], v[162:165], v[114:117]
	v_mfma_f32_16x16x32_bf16 v[114:117], v[158:161], v[166:169], v[114:117]
	v_mfma_f32_16x16x32_bf16 v[102:105], v[146:149], v[186:189], v[102:105]
	v_mfma_f32_16x16x32_bf16 v[102:105], v[150:153], v[190:193], v[102:105]
	v_mfma_f32_16x16x32_bf16 v[98:101], v[154:157], v[186:189], v[98:101]
	v_mfma_f32_16x16x32_bf16 v[98:101], v[158:161], v[190:193], v[98:101]
	v_mfma_f32_16x16x32_bf16 v[86:89], v[146:149], v[194:197], v[86:89]
	v_mfma_f32_16x16x32_bf16 v[86:89], v[150:153], v[198:201], v[86:89]
	v_mfma_f32_16x16x32_bf16 v[82:85], v[154:157], v[194:197], v[82:85]
	v_mfma_f32_16x16x32_bf16 v[82:85], v[158:161], v[198:201], v[82:85]
	v_mfma_f32_16x16x32_bf16 v[70:73], v[146:149], v[202:205], v[70:73]
	v_mfma_f32_16x16x32_bf16 v[70:73], v[150:153], v[206:209], v[70:73]
	v_mfma_f32_16x16x32_bf16 v[66:69], v[154:157], v[202:205], v[66:69]
	v_mfma_f32_16x16x32_bf16 v[66:69], v[158:161], v[206:209], v[66:69]
	s_barrier
	s_add_i32 s42, s76, s17
	v_lshl_add_u64 v[216:217], v[216:217], 0, s[8:9]
	s_mov_b32 m0, s42
	ds_read_b128 v[162:165], v214 offset:49152
	ds_read_b128 v[166:169], v214 offset:50176
	ds_read_b128 v[186:189], v214 offset:51200
	ds_read_b128 v[190:193], v214 offset:52224
	ds_read_b128 v[194:197], v214 offset:53248
	ds_read_b128 v[198:201], v214 offset:54272
	ds_read_b128 v[202:205], v214 offset:55296
	ds_read_b128 v[206:209], v214 offset:56320
	global_load_lds_dwordx4 v[216:217], off
	s_add_i32 m0, s42, 0x2000
	s_add_u32 s40, s40, 0x100080
	v_lshl_add_u64 v[216:217], v[218:219], 0, s[8:9]
	s_addc_u32 s41, s41, 0
	s_add_i32 s42, s77, s17
	global_load_lds_dwordx4 v[216:217], off
	v_lshl_add_u64 v[216:217], s[40:41], 0, v[172:173]
	s_mov_b32 m0, s42
	s_nop 0
	global_load_lds_dwordx4 v[216:217], off
	v_lshl_add_u64 v[216:217], s[40:41], 0, v[176:177]
	s_add_i32 m0, s42, 0x2000
	s_nop 0
	global_load_lds_dwordx4 v[216:217], off
	v_lshl_add_u64 v[216:217], v[220:221], 0, s[8:9]
	s_mov_b32 m0, s50
	s_nop 0
	global_load_lds_dwordx4 v[216:217], off
	v_lshl_add_u64 v[216:217], v[222:223], 0, s[8:9]
	s_mov_b32 m0, s51
	s_nop 0
	global_load_lds_dwordx4 v[216:217], off
	s_waitcnt vmcnt(8)
	s_waitcnt lgkmcnt(0)
	s_barrier
	v_mfma_f32_16x16x32_bf16 v[62:65], v[130:133], v[162:165], v[62:65]
	v_mfma_f32_16x16x32_bf16 v[62:65], v[134:137], v[166:169], v[62:65]
	v_mfma_f32_16x16x32_bf16 v[58:61], v[138:141], v[162:165], v[58:61]
	v_mfma_f32_16x16x32_bf16 v[58:61], v[142:145], v[166:169], v[58:61]
	v_mfma_f32_16x16x32_bf16 v[46:49], v[130:133], v[186:189], v[46:49]
	v_mfma_f32_16x16x32_bf16 v[46:49], v[134:137], v[190:193], v[46:49]
	v_mfma_f32_16x16x32_bf16 v[42:45], v[138:141], v[186:189], v[42:45]
	v_mfma_f32_16x16x32_bf16 v[42:45], v[142:145], v[190:193], v[42:45]
	v_mfma_f32_16x16x32_bf16 v[30:33], v[130:133], v[194:197], v[30:33]
	v_mfma_f32_16x16x32_bf16 v[30:33], v[134:137], v[198:201], v[30:33]
	v_mfma_f32_16x16x32_bf16 v[26:29], v[138:141], v[194:197], v[26:29]
	v_mfma_f32_16x16x32_bf16 v[26:29], v[142:145], v[198:201], v[26:29]
	v_mfma_f32_16x16x32_bf16 v[14:17], v[130:133], v[202:205], v[14:17]
	v_mfma_f32_16x16x32_bf16 v[14:17], v[134:137], v[206:209], v[14:17]
	v_mfma_f32_16x16x32_bf16 v[10:13], v[138:141], v[202:205], v[10:13]
	v_mfma_f32_16x16x32_bf16 v[10:13], v[142:145], v[206:209], v[10:13]
	v_mfma_f32_16x16x32_bf16 v[54:57], v[146:149], v[162:165], v[54:57]
	v_mfma_f32_16x16x32_bf16 v[54:57], v[150:153], v[166:169], v[54:57]
	v_mfma_f32_16x16x32_bf16 v[50:53], v[154:157], v[162:165], v[50:53]
	v_mfma_f32_16x16x32_bf16 v[50:53], v[158:161], v[166:169], v[50:53]
	v_mfma_f32_16x16x32_bf16 v[38:41], v[146:149], v[186:189], v[38:41]
	v_mfma_f32_16x16x32_bf16 v[38:41], v[150:153], v[190:193], v[38:41]
	v_mfma_f32_16x16x32_bf16 v[34:37], v[154:157], v[186:189], v[34:37]
	v_mfma_f32_16x16x32_bf16 v[34:37], v[158:161], v[190:193], v[34:37]
	v_mfma_f32_16x16x32_bf16 v[22:25], v[146:149], v[194:197], v[22:25]
	v_mfma_f32_16x16x32_bf16 v[22:25], v[150:153], v[198:201], v[22:25]
	v_mfma_f32_16x16x32_bf16 v[18:21], v[154:157], v[194:197], v[18:21]
	v_mfma_f32_16x16x32_bf16 v[18:21], v[158:161], v[198:201], v[18:21]
	v_mfma_f32_16x16x32_bf16 v[6:9], v[146:149], v[202:205], v[6:9]
	v_mfma_f32_16x16x32_bf16 v[6:9], v[150:153], v[206:209], v[6:9]
	v_mfma_f32_16x16x32_bf16 v[2:5], v[154:157], v[202:205], v[2:5]
	v_mfma_f32_16x16x32_bf16 v[2:5], v[158:161], v[206:209], v[2:5]
	s_barrier
	s_add_i32 s73, s73, 2
	s_add_u32 s38, s38, 0x100
	s_addc_u32 s39, s39, 0
	s_add_u32 s71, s71, 0x100
	s_addc_u32 s72, s72, 0
	s_cmp_gt_u32 s73, 61

.Lrlx6_0:
	s_waitcnt lgkmcnt(0)
	s_barrier
	v_mfma_i32_16x16x64_i8 v[118:121], v[130:133], v[186:189], 0
	v_mfma_i32_16x16x64_i8 v[118:121], v[134:137], v[190:193], v[118:121]
	v_mfma_i32_16x16x64_i8 v[102:105], v[162:165], v[186:189], 0
	v_mfma_i32_16x16x64_i8 v[102:105], v[166:169], v[190:193], v[102:105]
	v_mfma_i32_16x16x64_i8 v[114:117], v[130:133], v[194:197], 0
	v_mfma_i32_16x16x64_i8 v[114:117], v[134:137], v[198:201], v[114:117]
	v_mfma_i32_16x16x64_i8 v[98:101], v[162:165], v[194:197], 0
	v_mfma_i32_16x16x64_i8 v[98:101], v[166:169], v[198:201], v[98:101]
	v_mfma_i32_16x16x64_i8 v[126:129], v[130:133], v[202:205], 0
	v_mfma_i32_16x16x64_i8 v[126:129], v[134:137], v[206:209], v[126:129]
	v_mfma_i32_16x16x64_i8 v[110:113], v[162:165], v[202:205], 0
	v_mfma_i32_16x16x64_i8 v[110:113], v[166:169], v[206:209], v[110:113]
	v_mfma_i32_16x16x64_i8 v[122:125], v[130:133], v[210:213], 0
	v_mfma_i32_16x16x64_i8 v[122:125], v[134:137], v[214:217], v[122:125]
	v_mfma_i32_16x16x64_i8 v[106:109], v[162:165], v[210:213], 0
	v_mfma_i32_16x16x64_i8 v[106:109], v[166:169], v[214:217], v[106:109]
	v_mfma_i32_16x16x64_i8 v[86:89], v[170:173], v[186:189], 0
	v_mfma_i32_16x16x64_i8 v[86:89], v[174:177], v[190:193], v[86:89]
	v_mfma_i32_16x16x64_i8 v[70:73], v[178:181], v[186:189], 0
	v_mfma_i32_16x16x64_i8 v[70:73], v[182:185], v[190:193], v[70:73]
	v_mfma_i32_16x16x64_i8 v[82:85], v[170:173], v[194:197], 0
	v_mfma_i32_16x16x64_i8 v[82:85], v[174:177], v[198:201], v[82:85]
	v_mfma_i32_16x16x64_i8 v[66:69], v[178:181], v[194:197], 0
	v_mfma_i32_16x16x64_i8 v[66:69], v[182:185], v[198:201], v[66:69]
	v_mfma_i32_16x16x64_i8 v[94:97], v[170:173], v[202:205], 0
	v_mfma_i32_16x16x64_i8 v[94:97], v[174:177], v[206:209], v[94:97]
	v_mfma_i32_16x16x64_i8 v[78:81], v[178:181], v[202:205], 0
	v_mfma_i32_16x16x64_i8 v[78:81], v[182:185], v[206:209], v[78:81]
	v_mfma_i32_16x16x64_i8 v[90:93], v[170:173], v[210:213], 0
	v_mfma_i32_16x16x64_i8 v[90:93], v[174:177], v[214:217], v[90:93]
	v_mfma_i32_16x16x64_i8 v[74:77], v[178:181], v[210:213], 0
	v_mfma_i32_16x16x64_i8 v[74:77], v[182:185], v[214:217], v[74:77]
	s_barrier
	s_add_i32 s2, s82, s47
	v_lshl_add_u64 v[218:219], s[18:19], 0, v[144:145]
	s_mov_b32 m0, s2
	ds_read_b128 v[186:189], v236 offset:16384
	ds_read_b128 v[190:193], v236 offset:17408
	ds_read_b128 v[194:197], v236 offset:18432
	ds_read_b128 v[198:201], v236 offset:19456
	ds_read_b128 v[202:205], v236 offset:20480
	ds_read_b128 v[206:209], v236 offset:21504
	ds_read_b128 v[210:213], v236 offset:22528
	ds_read_b128 v[214:217], v236 offset:23552
	global_load_lds_dwordx4 v[218:219], off
	s_add_i32 m0, s2, 0x2000
	s_add_u32 s2, s18, 0x80000
	v_lshl_add_u64 v[220:221], s[18:19], 0, v[148:149]
	s_addc_u32 s3, s19, 0
	s_add_i32 s94, s16, s47
	global_load_lds_dwordx4 v[220:221], off
	v_lshl_add_u64 v[222:223], s[2:3], 0, v[144:145]
	s_mov_b32 m0, s94
	v_lshl_add_u64 v[224:225], s[42:43], 0, v[146:147]
	global_load_lds_dwordx4 v[222:223], off
	v_lshl_add_u64 v[222:223], s[2:3], 0, v[148:149]
	s_add_i32 m0, s94, 0x2000
	s_nop 0
	global_load_lds_dwordx4 v[222:223], off
	v_lshl_add_u64 v[222:223], s[42:43], 0, v[142:143]
	s_mov_b32 m0, s49
	s_nop 0
	global_load_lds_dwordx4 v[222:223], off
	s_mov_b32 m0, s50
	s_nop 0
	global_load_lds_dwordx4 v[224:225], off
	s_waitcnt vmcnt(24)
	s_cmp_lg_u32 s41, 0
	s_cbranch_scc1 .Lrlx6_1
	s_waitcnt vmcnt(8)
.Lrlx6_1:
	s_waitcnt lgkmcnt(0)
	s_barrier
	v_mfma_i32_16x16x64_i8 v[54:57], v[130:133], v[186:189], 0
	v_mfma_i32_16x16x64_i8 v[54:57], v[134:137], v[190:193], v[54:57]
	v_mfma_i32_16x16x64_i8 v[18:21], v[162:165], v[186:189], 0
	v_mfma_i32_16x16x64_i8 v[18:21], v[166:169], v[190:193], v[18:21]
	v_mfma_i32_16x16x64_i8 v[50:53], v[130:133], v[194:197], 0
	v_mfma_i32_16x16x64_i8 v[50:53], v[134:137], v[198:201], v[50:53]
	v_mfma_i32_16x16x64_i8 v[22:25], v[162:165], v[194:197], 0
	v_mfma_i32_16x16x64_i8 v[22:25], v[166:169], v[198:201], v[22:25]
	v_mfma_i32_16x16x64_i8 v[62:65], v[130:133], v[202:205], 0
	v_mfma_i32_16x16x64_i8 v[62:65], v[134:137], v[206:209], v[62:65]
	v_mfma_i32_16x16x64_i8 v[30:33], v[162:165], v[202:205], 0
	v_mfma_i32_16x16x64_i8 v[30:33], v[166:169], v[206:209], v[30:33]
	v_mfma_i32_16x16x64_i8 v[58:61], v[130:133], v[210:213], 0
	v_mfma_i32_16x16x64_i8 v[58:61], v[134:137], v[214:217], v[58:61]
	v_mfma_i32_16x16x64_i8 v[26:29], v[162:165], v[210:213], 0
	v_mfma_i32_16x16x64_i8 v[26:29], v[166:169], v[214:217], v[26:29]
	v_mfma_i32_16x16x64_i8 v[46:49], v[170:173], v[186:189], 0
	v_mfma_i32_16x16x64_i8 v[46:49], v[174:177], v[190:193], v[46:49]
	v_mfma_i32_16x16x64_i8 v[14:17], v[178:181], v[186:189], 0
	v_mfma_i32_16x16x64_i8 v[14:17], v[182:185], v[190:193], v[14:17]
	v_mfma_i32_16x16x64_i8 v[42:45], v[170:173], v[194:197], 0
	v_mfma_i32_16x16x64_i8 v[42:45], v[174:177], v[198:201], v[42:45]
	v_mfma_i32_16x16x64_i8 v[10:13], v[178:181], v[194:197], 0
	v_mfma_i32_16x16x64_i8 v[10:13], v[182:185], v[198:201], v[10:13]
	v_mfma_i32_16x16x64_i8 v[38:41], v[170:173], v[202:205], 0
	v_mfma_i32_16x16x64_i8 v[38:41], v[174:177], v[206:209], v[38:41]
	v_mfma_i32_16x16x64_i8 v[6:9], v[178:181], v[202:205], 0
	v_mfma_i32_16x16x64_i8 v[6:9], v[182:185], v[206:209], v[6:9]
	v_mfma_i32_16x16x64_i8 v[34:37], v[170:173], v[210:213], 0
	v_mfma_i32_16x16x64_i8 v[34:37], v[174:177], v[214:217], v[34:37]
	v_mfma_i32_16x16x64_i8 v[2:5], v[178:181], v[210:213], 0
	v_mfma_i32_16x16x64_i8 v[2:5], v[182:185], v[214:217], v[2:5]
	s_barrier
	s_add_i32 s94, 0, 0x18000
	s_add_i32 s95, 0, 0x1c000
	v_add_u32_e32 v166, s94, v232
	v_add_u32_e32 v182, s95, v232
	ds_read_b128 v[130:133], v166
	ds_read_b128 v[134:137], v166 offset:1024
	ds_read_b128 v[162:165], v166 offset:2048
	ds_read_b128 v[166:169], v166 offset:3072
	ds_read_b128 v[170:173], v182
	ds_read_b128 v[174:177], v182 offset:1024
	ds_read_b128 v[178:181], v182 offset:2048
	ds_read_b128 v[182:185], v182 offset:3072
	s_add_u32 s2, s42, 0x80000
	s_addc_u32 s3, s43, 0
	s_mov_b32 m0, s51
	v_lshl_add_u64 v[226:227], s[2:3], 0, v[142:143]
	ds_read_b128 v[186:189], v236 offset:32768
	ds_read_b128 v[190:193], v236 offset:33792
	ds_read_b128 v[194:197], v236 offset:34816
	ds_read_b128 v[198:201], v236 offset:35840
	ds_read_b128 v[202:205], v236 offset:36864
	ds_read_b128 v[206:209], v236 offset:37888
	ds_read_b128 v[210:213], v236 offset:38912
	ds_read_b128 v[214:217], v236 offset:39936
	global_load_lds_dwordx4 v[226:227], off
	v_lshl_add_u64 v[226:227], s[2:3], 0, v[146:147]
	s_mov_b32 m0, s54
	s_nop 0
	global_load_lds_dwordx4 v[226:227], off
	s_waitcnt vmcnt(8)
	s_waitcnt lgkmcnt(0)
	s_barrier
	v_mfma_i32_16x16x64_i8 v[118:121], v[130:133], v[186:189], v[118:121]
	v_mfma_i32_16x16x64_i8 v[118:121], v[134:137], v[190:193], v[118:121]
	v_mfma_i32_16x16x64_i8 v[102:105], v[162:165], v[186:189], v[102:105]
	v_mfma_i32_16x16x64_i8 v[102:105], v[166:169], v[190:193], v[102:105]
	v_mfma_i32_16x16x64_i8 v[114:117], v[130:133], v[194:197], v[114:117]
	v_mfma_i32_16x16x64_i8 v[114:117], v[134:137], v[198:201], v[114:117]
	v_mfma_i32_16x16x64_i8 v[98:101], v[162:165], v[194:197], v[98:101]
	v_mfma_i32_16x16x64_i8 v[98:101], v[166:169], v[198:201], v[98:101]
	v_mfma_i32_16x16x64_i8 v[126:129], v[130:133], v[202:205], v[126:129]
	v_mfma_i32_16x16x64_i8 v[126:129], v[134:137], v[206:209], v[126:129]
	v_mfma_i32_16x16x64_i8 v[110:113], v[162:165], v[202:205], v[110:113]
	v_mfma_i32_16x16x64_i8 v[110:113], v[166:169], v[206:209], v[110:113]
	v_mfma_i32_16x16x64_i8 v[122:125], v[130:133], v[210:213], v[122:125]
	v_mfma_i32_16x16x64_i8 v[122:125], v[134:137], v[214:217], v[122:125]
	v_mfma_i32_16x16x64_i8 v[106:109], v[162:165], v[210:213], v[106:109]
	v_mfma_i32_16x16x64_i8 v[106:109], v[166:169], v[214:217], v[106:109]
	v_mfma_i32_16x16x64_i8 v[86:89], v[170:173], v[186:189], v[86:89]
	v_mfma_i32_16x16x64_i8 v[86:89], v[174:177], v[190:193], v[86:89]
	v_mfma_i32_16x16x64_i8 v[70:73], v[178:181], v[186:189], v[70:73]
	v_mfma_i32_16x16x64_i8 v[70:73], v[182:185], v[190:193], v[70:73]
	v_mfma_i32_16x16x64_i8 v[82:85], v[170:173], v[194:197], v[82:85]
	v_mfma_i32_16x16x64_i8 v[82:85], v[174:177], v[198:201], v[82:85]
	v_mfma_i32_16x16x64_i8 v[66:69], v[178:181], v[194:197], v[66:69]
	v_mfma_i32_16x16x64_i8 v[66:69], v[182:185], v[198:201], v[66:69]
	v_mfma_i32_16x16x64_i8 v[94:97], v[170:173], v[202:205], v[94:97]
	v_mfma_i32_16x16x64_i8 v[94:97], v[174:177], v[206:209], v[94:97]
	v_mfma_i32_16x16x64_i8 v[78:81], v[178:181], v[202:205], v[78:81]
	v_mfma_i32_16x16x64_i8 v[78:81], v[182:185], v[206:209], v[78:81]
	v_mfma_i32_16x16x64_i8 v[90:93], v[170:173], v[210:213], v[90:93]
	v_mfma_i32_16x16x64_i8 v[90:93], v[174:177], v[214:217], v[90:93]
	v_mfma_i32_16x16x64_i8 v[74:77], v[178:181], v[210:213], v[74:77]
	v_mfma_i32_16x16x64_i8 v[74:77], v[182:185], v[214:217], v[74:77]
	s_barrier
	s_add_i32 s2, s94, s47
	v_lshl_add_u64 v[218:219], v[218:219], 0, s[14:15]
	s_mov_b32 m0, s2
	ds_read_b128 v[186:189], v236 offset:49152
	ds_read_b128 v[190:193], v236 offset:50176
	ds_read_b128 v[194:197], v236 offset:51200
	ds_read_b128 v[198:201], v236 offset:52224
	ds_read_b128 v[202:205], v236 offset:53248
	ds_read_b128 v[206:209], v236 offset:54272
	ds_read_b128 v[210:213], v236 offset:55296
	ds_read_b128 v[214:217], v236 offset:56320
	global_load_lds_dwordx4 v[218:219], off
	s_add_i32 m0, s2, 0x2000
	s_add_u32 s2, s18, 0x80080
	v_lshl_add_u64 v[218:219], v[220:221], 0, s[14:15]
	s_addc_u32 s3, s19, 0
	s_add_i32 s18, s95, s47
	global_load_lds_dwordx4 v[218:219], off
	v_lshl_add_u64 v[218:219], s[2:3], 0, v[144:145]
	s_mov_b32 m0, s18
	s_nop 0
	global_load_lds_dwordx4 v[218:219], off
	v_lshl_add_u64 v[218:219], s[2:3], 0, v[148:149]
	s_add_i32 m0, s18, 0x2000
	s_nop 0
	global_load_lds_dwordx4 v[218:219], off
	v_lshl_add_u64 v[218:219], v[222:223], 0, s[14:15]
	s_mov_b32 m0, s63
	s_nop 0
	global_load_lds_dwordx4 v[218:219], off
	v_lshl_add_u64 v[218:219], v[224:225], 0, s[14:15]
	s_mov_b32 m0, s64
	s_nop 0
	global_load_lds_dwordx4 v[218:219], off
	s_waitcnt vmcnt(8)
	s_waitcnt lgkmcnt(0)
	s_barrier
	v_mfma_i32_16x16x64_i8 v[54:57], v[130:133], v[186:189], v[54:57]
	v_mfma_i32_16x16x64_i8 v[54:57], v[134:137], v[190:193], v[54:57]
	v_mfma_i32_16x16x64_i8 v[18:21], v[162:165], v[186:189], v[18:21]
	v_mfma_i32_16x16x64_i8 v[18:21], v[166:169], v[190:193], v[18:21]
	v_mfma_i32_16x16x64_i8 v[50:53], v[130:133], v[194:197], v[50:53]
	v_mfma_i32_16x16x64_i8 v[50:53], v[134:137], v[198:201], v[50:53]
	v_mfma_i32_16x16x64_i8 v[22:25], v[162:165], v[194:197], v[22:25]
	v_mfma_i32_16x16x64_i8 v[22:25], v[166:169], v[198:201], v[22:25]
	v_mfma_i32_16x16x64_i8 v[62:65], v[130:133], v[202:205], v[62:65]
	v_mfma_i32_16x16x64_i8 v[62:65], v[134:137], v[206:209], v[62:65]
	v_mfma_i32_16x16x64_i8 v[30:33], v[162:165], v[202:205], v[30:33]
	v_mfma_i32_16x16x64_i8 v[30:33], v[166:169], v[206:209], v[30:33]
	v_mfma_i32_16x16x64_i8 v[58:61], v[130:133], v[210:213], v[58:61]
	v_mfma_i32_16x16x64_i8 v[58:61], v[134:137], v[214:217], v[58:61]
	v_mfma_i32_16x16x64_i8 v[26:29], v[162:165], v[210:213], v[26:29]
	v_mfma_i32_16x16x64_i8 v[26:29], v[166:169], v[214:217], v[26:29]
	v_mfma_i32_16x16x64_i8 v[46:49], v[170:173], v[186:189], v[46:49]
	v_mfma_i32_16x16x64_i8 v[46:49], v[174:177], v[190:193], v[46:49]
	v_mfma_i32_16x16x64_i8 v[14:17], v[178:181], v[186:189], v[14:17]
	v_mfma_i32_16x16x64_i8 v[14:17], v[182:185], v[190:193], v[14:17]
	v_mfma_i32_16x16x64_i8 v[42:45], v[170:173], v[194:197], v[42:45]
	v_mfma_i32_16x16x64_i8 v[42:45], v[174:177], v[198:201], v[42:45]
	v_mfma_i32_16x16x64_i8 v[10:13], v[178:181], v[194:197], v[10:13]
	v_mfma_i32_16x16x64_i8 v[10:13], v[182:185], v[198:201], v[10:13]
	v_mfma_i32_16x16x64_i8 v[38:41], v[170:173], v[202:205], v[38:41]
	v_mfma_i32_16x16x64_i8 v[38:41], v[174:177], v[206:209], v[38:41]
	v_mfma_i32_16x16x64_i8 v[6:9], v[178:181], v[202:205], v[6:9]
	v_mfma_i32_16x16x64_i8 v[6:9], v[182:185], v[206:209], v[6:9]
	v_mfma_i32_16x16x64_i8 v[34:37], v[170:173], v[210:213], v[34:37]
	v_mfma_i32_16x16x64_i8 v[34:37], v[174:177], v[214:217], v[34:37]
	v_mfma_i32_16x16x64_i8 v[2:5], v[178:181], v[210:213], v[2:5]
	v_mfma_i32_16x16x64_i8 v[2:5], v[182:185], v[214:217], v[2:5]
	s_barrier
	s_add_i32 s93, s93, 2
	s_add_u32 s91, s91, 0x100
	s_addc_u32 s92, s92, 0
	s_cmp_gt_u32 s93, 29
	s_mov_b64 s[2:3], s[4:5]

.Lrlx7_0:
	s_waitcnt lgkmcnt(0)
	s_barrier
	v_mfma_f32_16x16x32_bf16 v[126:129], v[130:133], v[162:165], 0
	v_mfma_f32_16x16x32_bf16 v[126:129], v[134:137], v[166:169], v[126:129]
	v_mfma_f32_16x16x32_bf16 v[122:125], v[138:141], v[162:165], 0
	v_mfma_f32_16x16x32_bf16 v[122:125], v[142:145], v[166:169], v[122:125]
	v_mfma_f32_16x16x32_bf16 v[110:113], v[130:133], v[186:189], 0
	v_mfma_f32_16x16x32_bf16 v[110:113], v[134:137], v[190:193], v[110:113]
	v_mfma_f32_16x16x32_bf16 v[106:109], v[138:141], v[186:189], 0
	v_mfma_f32_16x16x32_bf16 v[106:109], v[142:145], v[190:193], v[106:109]
	v_mfma_f32_16x16x32_bf16 v[94:97], v[130:133], v[194:197], 0
	v_mfma_f32_16x16x32_bf16 v[94:97], v[134:137], v[198:201], v[94:97]
	v_mfma_f32_16x16x32_bf16 v[90:93], v[138:141], v[194:197], 0
	v_mfma_f32_16x16x32_bf16 v[90:93], v[142:145], v[198:201], v[90:93]
	v_mfma_f32_16x16x32_bf16 v[78:81], v[130:133], v[202:205], 0
	v_mfma_f32_16x16x32_bf16 v[78:81], v[134:137], v[206:209], v[78:81]
	v_mfma_f32_16x16x32_bf16 v[74:77], v[138:141], v[202:205], 0
	v_mfma_f32_16x16x32_bf16 v[74:77], v[142:145], v[206:209], v[74:77]
	v_mfma_f32_16x16x32_bf16 v[118:121], v[146:149], v[162:165], 0
	v_mfma_f32_16x16x32_bf16 v[118:121], v[150:153], v[166:169], v[118:121]
	v_mfma_f32_16x16x32_bf16 v[114:117], v[154:157], v[162:165], 0
	v_mfma_f32_16x16x32_bf16 v[114:117], v[158:161], v[166:169], v[114:117]
	v_mfma_f32_16x16x32_bf16 v[102:105], v[146:149], v[186:189], 0
	v_mfma_f32_16x16x32_bf16 v[102:105], v[150:153], v[190:193], v[102:105]
	v_mfma_f32_16x16x32_bf16 v[98:101], v[154:157], v[186:189], 0
	v_mfma_f32_16x16x32_bf16 v[98:101], v[158:161], v[190:193], v[98:101]
	v_mfma_f32_16x16x32_bf16 v[86:89], v[146:149], v[194:197], 0
	v_mfma_f32_16x16x32_bf16 v[86:89], v[150:153], v[198:201], v[86:89]
	v_mfma_f32_16x16x32_bf16 v[82:85], v[154:157], v[194:197], 0
	v_mfma_f32_16x16x32_bf16 v[82:85], v[158:161], v[198:201], v[82:85]
	v_mfma_f32_16x16x32_bf16 v[70:73], v[146:149], v[202:205], 0
	v_mfma_f32_16x16x32_bf16 v[70:73], v[150:153], v[206:209], v[70:73]
	v_mfma_f32_16x16x32_bf16 v[66:69], v[154:157], v[202:205], 0
	v_mfma_f32_16x16x32_bf16 v[66:69], v[158:161], v[206:209], v[66:69]
	s_barrier
	s_add_i32 s18, s56, s43
	v_lshl_add_u64 v[216:217], s[38:39], 0, v[172:173]
	s_mov_b32 m0, s18
	ds_read_b128 v[162:165], v214 offset:16384
	ds_read_b128 v[166:169], v214 offset:17408
	ds_read_b128 v[186:189], v214 offset:18432
	ds_read_b128 v[190:193], v214 offset:19456
	ds_read_b128 v[194:197], v214 offset:20480
	ds_read_b128 v[198:201], v214 offset:21504
	ds_read_b128 v[202:205], v214 offset:22528
	ds_read_b128 v[206:209], v214 offset:23552
	global_load_lds_dwordx4 v[216:217], off
	s_add_i32 m0, s18, 0x2000
	s_add_u32 s18, s38, 0x380000
	v_lshl_add_u64 v[218:219], s[38:39], 0, v[176:177]
	s_addc_u32 s19, s39, 0
	s_add_i32 s72, s57, s43
	global_load_lds_dwordx4 v[218:219], off
	v_lshl_add_u64 v[220:221], s[18:19], 0, v[172:173]
	s_mov_b32 m0, s72
	v_lshl_add_u64 v[222:223], s[40:41], 0, v[174:175]
	global_load_lds_dwordx4 v[220:221], off
	v_lshl_add_u64 v[220:221], s[18:19], 0, v[176:177]
	s_add_i32 m0, s72, 0x2000
	s_nop 0
	global_load_lds_dwordx4 v[220:221], off
	v_lshl_add_u64 v[220:221], s[40:41], 0, v[170:171]
	s_mov_b32 m0, s44
	s_nop 0
	global_load_lds_dwordx4 v[220:221], off
	s_mov_b32 m0, s45
	s_nop 0
	global_load_lds_dwordx4 v[222:223], off
	s_waitcnt vmcnt(24)
	s_cmp_lg_u32 s48, 1
	s_cbranch_scc1 .Lrlx7_1
	s_waitcnt vmcnt(8)
.Lrlx7_1:
	s_waitcnt lgkmcnt(0)
	s_barrier
	v_mfma_f32_16x16x32_bf16 v[62:65], v[130:133], v[162:165], 0
	v_mfma_f32_16x16x32_bf16 v[62:65], v[134:137], v[166:169], v[62:65]
	v_mfma_f32_16x16x32_bf16 v[58:61], v[138:141], v[162:165], 0
	v_mfma_f32_16x16x32_bf16 v[58:61], v[142:145], v[166:169], v[58:61]
	v_mfma_f32_16x16x32_bf16 v[46:49], v[130:133], v[186:189], 0
	v_mfma_f32_16x16x32_bf16 v[46:49], v[134:137], v[190:193], v[46:49]
	v_mfma_f32_16x16x32_bf16 v[42:45], v[138:141], v[186:189], 0
	v_mfma_f32_16x16x32_bf16 v[42:45], v[142:145], v[190:193], v[42:45]
	v_mfma_f32_16x16x32_bf16 v[30:33], v[130:133], v[194:197], 0
	v_mfma_f32_16x16x32_bf16 v[30:33], v[134:137], v[198:201], v[30:33]
	v_mfma_f32_16x16x32_bf16 v[26:29], v[138:141], v[194:197], 0
	v_mfma_f32_16x16x32_bf16 v[26:29], v[142:145], v[198:201], v[26:29]
	v_mfma_f32_16x16x32_bf16 v[14:17], v[130:133], v[202:205], 0
	v_mfma_f32_16x16x32_bf16 v[14:17], v[134:137], v[206:209], v[14:17]
	v_mfma_f32_16x16x32_bf16 v[10:13], v[138:141], v[202:205], 0
	v_mfma_f32_16x16x32_bf16 v[10:13], v[142:145], v[206:209], v[10:13]
	v_mfma_f32_16x16x32_bf16 v[54:57], v[146:149], v[162:165], 0
	v_mfma_f32_16x16x32_bf16 v[54:57], v[150:153], v[166:169], v[54:57]
	v_mfma_f32_16x16x32_bf16 v[50:53], v[154:157], v[162:165], 0
	v_mfma_f32_16x16x32_bf16 v[50:53], v[158:161], v[166:169], v[50:53]
	v_mfma_f32_16x16x32_bf16 v[38:41], v[146:149], v[186:189], 0
	v_mfma_f32_16x16x32_bf16 v[38:41], v[150:153], v[190:193], v[38:41]
	v_mfma_f32_16x16x32_bf16 v[34:37], v[154:157], v[186:189], 0
	v_mfma_f32_16x16x32_bf16 v[34:37], v[158:161], v[190:193], v[34:37]
	v_mfma_f32_16x16x32_bf16 v[22:25], v[146:149], v[194:197], 0
	v_mfma_f32_16x16x32_bf16 v[22:25], v[150:153], v[198:201], v[22:25]
	v_mfma_f32_16x16x32_bf16 v[18:21], v[154:157], v[194:197], 0
	v_mfma_f32_16x16x32_bf16 v[18:21], v[158:161], v[198:201], v[18:21]
	v_mfma_f32_16x16x32_bf16 v[6:9], v[146:149], v[202:205], 0
	v_mfma_f32_16x16x32_bf16 v[6:9], v[150:153], v[206:209], v[6:9]
	v_mfma_f32_16x16x32_bf16 v[2:5], v[154:157], v[202:205], 0
	v_mfma_f32_16x16x32_bf16 v[2:5], v[158:161], v[206:209], v[2:5]
	s_barrier
	s_add_i32 s72, 0, 0x18000
	s_add_i32 s73, 0, 0x1c000
	v_add_u32_e32 v142, s72, v211
	v_add_u32_e32 v158, s73, v211
	ds_read_b128 v[130:133], v142
	ds_read_b128 v[134:137], v142 offset:1024
	ds_read_b128 v[138:141], v142 offset:2048
	ds_read_b128 v[142:145], v142 offset:3072
	ds_read_b128 v[146:149], v158
	ds_read_b128 v[150:153], v158 offset:1024
	ds_read_b128 v[154:157], v158 offset:2048
	ds_read_b128 v[158:161], v158 offset:3072
	s_add_u32 s18, s40, 0x380000
	s_addc_u32 s19, s41, 0
	s_mov_b32 m0, s46
	v_lshl_add_u64 v[224:225], s[18:19], 0, v[170:171]
	ds_read_b128 v[162:165], v214 offset:32768
	ds_read_b128 v[166:169], v214 offset:33792
	ds_read_b128 v[186:189], v214 offset:34816
	ds_read_b128 v[190:193], v214 offset:35840
	ds_read_b128 v[194:197], v214 offset:36864
	ds_read_b128 v[198:201], v214 offset:37888
	ds_read_b128 v[202:205], v214 offset:38912
	ds_read_b128 v[206:209], v214 offset:39936
	global_load_lds_dwordx4 v[224:225], off
	v_lshl_add_u64 v[224:225], s[18:19], 0, v[174:175]
	s_mov_b32 m0, s47
	s_nop 0
	global_load_lds_dwordx4 v[224:225], off
	s_waitcnt vmcnt(8)
	s_waitcnt lgkmcnt(0)
	s_barrier
	v_mfma_f32_16x16x32_bf16 v[126:129], v[130:133], v[162:165], v[126:129]
	v_mfma_f32_16x16x32_bf16 v[126:129], v[134:137], v[166:169], v[126:129]
	v_mfma_f32_16x16x32_bf16 v[122:125], v[138:141], v[162:165], v[122:125]
	v_mfma_f32_16x16x32_bf16 v[122:125], v[142:145], v[166:169], v[122:125]
	v_mfma_f32_16x16x32_bf16 v[110:113], v[130:133], v[186:189], v[110:113]
	v_mfma_f32_16x16x32_bf16 v[110:113], v[134:137], v[190:193], v[110:113]
	v_mfma_f32_16x16x32_bf16 v[106:109], v[138:141], v[186:189], v[106:109]
	v_mfma_f32_16x16x32_bf16 v[106:109], v[142:145], v[190:193], v[106:109]
	v_mfma_f32_16x16x32_bf16 v[94:97], v[130:133], v[194:197], v[94:97]
	v_mfma_f32_16x16x32_bf16 v[94:97], v[134:137], v[198:201], v[94:97]
	v_mfma_f32_16x16x32_bf16 v[90:93], v[138:141], v[194:197], v[90:93]
	v_mfma_f32_16x16x32_bf16 v[90:93], v[142:145], v[198:201], v[90:93]
	v_mfma_f32_16x16x32_bf16 v[78:81], v[130:133], v[202:205], v[78:81]
	v_mfma_f32_16x16x32_bf16 v[78:81], v[134:137], v[206:209], v[78:81]
	v_mfma_f32_16x16x32_bf16 v[74:77], v[138:141], v[202:205], v[74:77]
	v_mfma_f32_16x16x32_bf16 v[74:77], v[142:145], v[206:209], v[74:77]
	v_mfma_f32_16x16x32_bf16 v[118:121], v[146:149], v[162:165], v[118:121]
	v_mfma_f32_16x16x32_bf16 v[118:121], v[150:153], v[166:169], v[118:121]
	v_mfma_f32_16x16x32_bf16 v[114:117], v[154:157], v[162:165], v[114:117]
	v_mfma_f32_16x16x32_bf16 v[114:117], v[158:161], v[166:169], v[114:117]
	v_mfma_f32_16x16x32_bf16 v[102:105], v[146:149], v[186:189], v[102:105]
	v_mfma_f32_16x16x32_bf16 v[102:105], v[150:153], v[190:193], v[102:105]
	v_mfma_f32_16x16x32_bf16 v[98:101], v[154:157], v[186:189], v[98:101]
	v_mfma_f32_16x16x32_bf16 v[98:101], v[158:161], v[190:193], v[98:101]
	v_mfma_f32_16x16x32_bf16 v[86:89], v[146:149], v[194:197], v[86:89]
	v_mfma_f32_16x16x32_bf16 v[86:89], v[150:153], v[198:201], v[86:89]
	v_mfma_f32_16x16x32_bf16 v[82:85], v[154:157], v[194:197], v[82:85]
	v_mfma_f32_16x16x32_bf16 v[82:85], v[158:161], v[198:201], v[82:85]
	v_mfma_f32_16x16x32_bf16 v[70:73], v[146:149], v[202:205], v[70:73]
	v_mfma_f32_16x16x32_bf16 v[70:73], v[150:153], v[206:209], v[70:73]
	v_mfma_f32_16x16x32_bf16 v[66:69], v[154:157], v[202:205], v[66:69]
	v_mfma_f32_16x16x32_bf16 v[66:69], v[158:161], v[206:209], v[66:69]
	s_barrier
	s_add_i32 s18, s72, s43
	v_lshl_add_u64 v[216:217], v[216:217], 0, s[8:9]
	s_mov_b32 m0, s18
	ds_read_b128 v[162:165], v214 offset:49152
	ds_read_b128 v[166:169], v214 offset:50176
	ds_read_b128 v[186:189], v214 offset:51200
	ds_read_b128 v[190:193], v214 offset:52224
	ds_read_b128 v[194:197], v214 offset:53248
	ds_read_b128 v[198:201], v214 offset:54272
	ds_read_b128 v[202:205], v214 offset:55296
	ds_read_b128 v[206:209], v214 offset:56320
	global_load_lds_dwordx4 v[216:217], off
	s_add_i32 m0, s18, 0x2000
	s_add_u32 s18, s38, 0x380080
	v_lshl_add_u64 v[216:217], v[218:219], 0, s[8:9]
	s_addc_u32 s19, s39, 0
	s_add_i32 s38, s73, s43
	global_load_lds_dwordx4 v[216:217], off
	v_lshl_add_u64 v[216:217], s[18:19], 0, v[172:173]
	s_mov_b32 m0, s38
	s_nop 0
	global_load_lds_dwordx4 v[216:217], off
	v_lshl_add_u64 v[216:217], s[18:19], 0, v[176:177]
	s_add_i32 m0, s38, 0x2000
	s_nop 0
	global_load_lds_dwordx4 v[216:217], off
	v_lshl_add_u64 v[216:217], v[220:221], 0, s[8:9]
	s_mov_b32 m0, s51
	s_nop 0
	global_load_lds_dwordx4 v[216:217], off
	v_lshl_add_u64 v[216:217], v[222:223], 0, s[8:9]
	s_mov_b32 m0, s54
	s_nop 0
	global_load_lds_dwordx4 v[216:217], off
	s_waitcnt vmcnt(8)
	s_waitcnt lgkmcnt(0)
	s_barrier
	v_mfma_f32_16x16x32_bf16 v[62:65], v[130:133], v[162:165], v[62:65]
	v_mfma_f32_16x16x32_bf16 v[62:65], v[134:137], v[166:169], v[62:65]
	v_mfma_f32_16x16x32_bf16 v[58:61], v[138:141], v[162:165], v[58:61]
	v_mfma_f32_16x16x32_bf16 v[58:61], v[142:145], v[166:169], v[58:61]
	v_mfma_f32_16x16x32_bf16 v[46:49], v[130:133], v[186:189], v[46:49]
	v_mfma_f32_16x16x32_bf16 v[46:49], v[134:137], v[190:193], v[46:49]
	v_mfma_f32_16x16x32_bf16 v[42:45], v[138:141], v[186:189], v[42:45]
	v_mfma_f32_16x16x32_bf16 v[42:45], v[142:145], v[190:193], v[42:45]
	v_mfma_f32_16x16x32_bf16 v[30:33], v[130:133], v[194:197], v[30:33]
	v_mfma_f32_16x16x32_bf16 v[30:33], v[134:137], v[198:201], v[30:33]
	v_mfma_f32_16x16x32_bf16 v[26:29], v[138:141], v[194:197], v[26:29]
	v_mfma_f32_16x16x32_bf16 v[26:29], v[142:145], v[198:201], v[26:29]
	v_mfma_f32_16x16x32_bf16 v[14:17], v[130:133], v[202:205], v[14:17]
	v_mfma_f32_16x16x32_bf16 v[14:17], v[134:137], v[206:209], v[14:17]
	v_mfma_f32_16x16x32_bf16 v[10:13], v[138:141], v[202:205], v[10:13]
	v_mfma_f32_16x16x32_bf16 v[10:13], v[142:145], v[206:209], v[10:13]
	v_mfma_f32_16x16x32_bf16 v[54:57], v[146:149], v[162:165], v[54:57]
	v_mfma_f32_16x16x32_bf16 v[54:57], v[150:153], v[166:169], v[54:57]
	v_mfma_f32_16x16x32_bf16 v[50:53], v[154:157], v[162:165], v[50:53]
	v_mfma_f32_16x16x32_bf16 v[50:53], v[158:161], v[166:169], v[50:53]
	v_mfma_f32_16x16x32_bf16 v[38:41], v[146:149], v[186:189], v[38:41]
	v_mfma_f32_16x16x32_bf16 v[38:41], v[150:153], v[190:193], v[38:41]
	v_mfma_f32_16x16x32_bf16 v[34:37], v[154:157], v[186:189], v[34:37]
	v_mfma_f32_16x16x32_bf16 v[34:37], v[158:161], v[190:193], v[34:37]
	v_mfma_f32_16x16x32_bf16 v[22:25], v[146:149], v[194:197], v[22:25]
	v_mfma_f32_16x16x32_bf16 v[22:25], v[150:153], v[198:201], v[22:25]
	v_mfma_f32_16x16x32_bf16 v[18:21], v[154:157], v[194:197], v[18:21]
	v_mfma_f32_16x16x32_bf16 v[18:21], v[158:161], v[198:201], v[18:21]
	v_mfma_f32_16x16x32_bf16 v[6:9], v[146:149], v[202:205], v[6:9]
	v_mfma_f32_16x16x32_bf16 v[6:9], v[150:153], v[206:209], v[6:9]
	v_mfma_f32_16x16x32_bf16 v[2:5], v[154:157], v[202:205], v[2:5]
	v_mfma_f32_16x16x32_bf16 v[2:5], v[158:161], v[206:209], v[2:5]
	s_barrier
	s_add_i32 s71, s71, 2
	s_add_u32 s69, s69, 0x100
	s_addc_u32 s70, s70, 0
	s_cmpk_gt_u32 s71, 0xdd
	s_mov_b64 s[18:19], s[36:37]
